# adds: pool-mixer previous-row loads prefetched, first-layer pool GEMM residual prefetch 4 groups deep, spatial bias loads hoisted
# speedup vs baseline: 1.0250x; 1.0045x over previous
.LBB0_459:
	s_mov_b32 s6, -1
	s_lshl_b32 s5, s5, 8
	v_mbcnt_lo_u32_b32 v134, s6, 0
	v_mbcnt_hi_u32_b32 v134, s6, v134
	s_getreg_b32 s6, hwreg(HW_REG_HW_ID, 0, 6)
	s_and_b32 s6, s6, 63
	s_lshl_b32 s6, s6, 2
	s_add_i32 s6, s6, 0
	s_add_i32 s6, s6, 0x20200
	v_mov_b32_e32 v135, s6
	ds_read_b32 v135, v135
	v_bfrev_b32_e32 v143, 0.5
	s_movk_i32 s84, 0x80
	s_waitcnt lgkmcnt(0)
	v_readfirstlane_b32 s6, v135
	s_nop 1
	v_lshl_add_u32 v137, s6, 6, v134
	s_nop 0
	v_readfirstlane_b32 s6, v137
	s_bfe_u32 s10, s6, 0x20006
	s_ashr_i32 s6, s6, 2
	s_andn2_b32 s6, s6, 63
	s_add_i32 s6, s6, s5
	v_bfe_u32 v142, v137, 4, 2
	v_and_or_b32 v136, v137, 15, s6
	s_lshl_b32 s5, s4, 8
	s_lshl_b32 s6, s10, 5
	v_lshlrev_b32_e32 v137, 2, v137
	s_or_b32 s5, s6, s5
	v_bitop3_b32 v158, v137, 64, v143 bitop3:0x6c
	v_bitop3_b32 v159, v137, s84, v143 bitop3:0x6c
	v_ashrrev_i32_e32 v137, 31, v136
	v_lshl_or_b32 v134, v142, 3, s5
	v_cmp_eq_u32_e32 vcc, 0, v142
	v_lshlrev_b64 v[142:143], 12, v[136:137]
	v_ashrrev_i32_e32 v135, 31, v134
	v_lshl_add_u64 v[142:143], s[44:45], 0, v[142:143]
	v_lshl_add_u64 v[154:155], v[134:135], 2, v[142:143]
	v_mov_b32_e32 v162, v154
	v_mov_b32_e32 v163, v155
	global_load_dwordx4 v[142:145], v[154:155], off offset:16
	global_load_dwordx4 v[146:149], v[154:155], off
	global_load_dwordx4 v[150:153], v[154:155], off offset:528
	s_nop 0
	global_load_dwordx4 v[154:157], v[154:155], off offset:512
	s_mov_b64 s[100:101], 0x10000
	v_lshl_add_u64 v[164:165], v[162:163], 0, s[100:101]
	global_load_dwordx4 v[168:171], v[164:165], off
	global_load_dwordx4 v[172:175], v[164:165], off offset:16
	global_load_dwordx4 v[176:179], v[164:165], off offset:512
	global_load_dwordx4 v[180:183], v[164:165], off offset:528
	s_mov_b64 s[100:101], 0x20000
	v_lshl_add_u64 v[164:165], v[162:163], 0, s[100:101]
	global_load_dwordx4 v[184:187], v[164:165], off
	global_load_dwordx4 v[188:191], v[164:165], off offset:16
	global_load_dwordx4 v[192:195], v[164:165], off offset:512
	global_load_dwordx4 v[208:211], v[164:165], off offset:528
	s_mov_b64 s[100:101], 0x30000
	v_lshl_add_u64 v[164:165], v[162:163], 0, s[100:101]
	global_load_dwordx4 v[212:215], v[164:165], off
	global_load_dwordx4 v[216:219], v[164:165], off offset:16
	global_load_dwordx4 v[220:223], v[164:165], off offset:512
	global_load_dwordx4 v[224:227], v[164:165], off offset:528
	s_mov_b64 s[100:101], 0x80000
	v_lshl_add_u64 v[164:165], v[162:163], 0, s[100:101]
	global_load_dwordx4 v[228:231], v[164:165], off
	global_load_dwordx4 v[232:235], v[164:165], off offset:16
	global_load_dwordx4 v[236:239], v[164:165], off offset:512
	global_load_dwordx4 v[240:243], v[164:165], off offset:528
	v_lshlrev_b64 v[160:161], 11, v[136:137]
	s_lshl_b32 s6, s4, 2
	s_ashr_i32 s7, s6, 31
	s_waitcnt vmcnt(16)
	v_pk_add_f32 v[124:125], v[124:125], v[142:143]
	v_pk_add_f32 v[122:123], v[122:123], v[148:149]
	v_pk_add_f32 v[120:121], v[120:121], v[146:147]
	v_pk_add_f32 v[126:127], v[126:127], v[144:145]
	v_cvt_pk_bf16_f32 v120, v120, v121
	v_cvt_pk_bf16_f32 v121, v122, v123
	v_cvt_pk_bf16_f32 v122, v124, v125
	v_lshl_add_u64 v[124:125], s[68:69], 0, v[160:161]
	v_lshl_add_u64 v[124:125], v[134:135], 1, v[124:125]
	v_cvt_pk_bf16_f32 v123, v126, v127
	global_store_dwordx4 v[124:125], v[120:123], off nt
	v_lshlrev_b32_e32 v126, 16, v120
	v_pk_add_f32 v[116:117], v[116:117], v[154:155]
	v_and_b32_e32 v120, 0xffff0000, v120
	v_mul_f32_e32 v120, v120, v120
	v_fmac_f32_e32 v120, v126, v126
	v_lshlrev_b32_e32 v126, 16, v121
	v_and_b32_e32 v121, 0xffff0000, v121
	v_mul_f32_e32 v121, v121, v121
	v_fmac_f32_e32 v121, v126, v126
	v_add_f32_e32 v120, v120, v121
	v_lshlrev_b32_e32 v121, 16, v122
	v_and_b32_e32 v122, 0xffff0000, v122
	v_mul_f32_e32 v122, v122, v122
	v_fmac_f32_e32 v122, v121, v121
	v_add_f32_e32 v120, v120, v122
	v_and_b32_e32 v122, 0xffff0000, v123
	v_lshlrev_b32_e32 v121, 16, v123
	v_mul_f32_e32 v122, v122, v122
	v_fmac_f32_e32 v122, v121, v121
	v_add_f32_e32 v122, v120, v122
	v_pk_add_f32 v[120:121], v[114:115], v[152:153]
	v_pk_add_f32 v[114:115], v[112:113], v[150:151]
	v_cvt_pk_bf16_f32 v112, v116, v117
	v_pk_add_f32 v[118:119], v[118:119], v[156:157]
	v_lshlrev_b32_e32 v116, 16, v112
	v_cvt_pk_bf16_f32 v113, v118, v119
	v_cvt_pk_bf16_f32 v114, v114, v115
	v_cvt_pk_bf16_f32 v115, v120, v121
	global_store_dwordx4 v[124:125], v[112:115], off offset:256 nt
	s_nop 1
	v_and_b32_e32 v112, 0xffff0000, v112
	v_mul_f32_e32 v112, v112, v112
	v_fmac_f32_e32 v112, v116, v116
	v_lshlrev_b32_e32 v116, 16, v113
	v_and_b32_e32 v113, 0xffff0000, v113
	v_mul_f32_e32 v113, v113, v113
	v_add_f32_e32 v112, v122, v112
	v_fmac_f32_e32 v113, v116, v116
	v_add_f32_e32 v112, v112, v113
	v_lshlrev_b32_e32 v113, 16, v114
	v_and_b32_e32 v114, 0xffff0000, v114
	v_mul_f32_e32 v114, v114, v114
	v_fmac_f32_e32 v114, v113, v113
	v_add_f32_e32 v112, v112, v114
	v_and_b32_e32 v114, 0xffff0000, v115
	v_lshlrev_b32_e32 v113, 16, v115
	v_mul_f32_e32 v114, v114, v114
	v_fmac_f32_e32 v114, v113, v113
	v_add_f32_e32 v112, v112, v114
	ds_bpermute_b32 v113, v158, v112
	s_waitcnt lgkmcnt(0)
	v_add_f32_e32 v112, v112, v113
	ds_bpermute_b32 v113, v159, v112
	s_and_saveexec_b64 s[8:9], vcc
	s_cbranch_execz .LBB0_461
	v_lshlrev_b64 v[114:115], 6, v[136:137]
	v_lshl_add_u64 v[114:115], s[66:67], 0, v[114:115]
	v_lshl_add_u64 v[114:115], s[6:7], 2, v[114:115]
	s_lshl_b32 s38, s10, 2
	v_lshl_add_u64 v[114:115], v[114:115], 0, s[38:39]
	s_waitcnt lgkmcnt(0)
	v_add_f32_e32 v112, v112, v113
	global_store_dword v[114:115], v112, off
.LBB0_461:
	s_or_b64 exec, exec, s[8:9]
	v_or_b32_e32 v112, 16, v136
	s_waitcnt lgkmcnt(0)
	v_ashrrev_i32_e32 v113, 31, v112
	v_lshlrev_b64 v[114:115], 12, v[112:113]
	v_lshl_add_u64 v[114:115], s[44:45], 0, v[114:115]
	v_lshl_add_u64 v[126:127], v[134:135], 2, v[114:115]
	v_lshlrev_b64 v[126:127], 11, v[112:113]
	v_lshl_add_u64 v[126:127], s[68:69], 0, v[126:127]
	v_lshl_add_u64 v[126:127], v[134:135], 1, v[126:127]
	s_waitcnt vmcnt(15)
	v_mov_b32_e32 v114, v168
	v_mov_b32_e32 v115, v169
	v_mov_b32_e32 v116, v170
	v_mov_b32_e32 v117, v171
	v_mov_b32_e32 v118, v172
	v_mov_b32_e32 v119, v173
	v_mov_b32_e32 v120, v174
	v_mov_b32_e32 v121, v175
	v_mov_b32_e32 v122, v176
	v_mov_b32_e32 v123, v177
	v_mov_b32_e32 v124, v178
	v_mov_b32_e32 v125, v179
	v_mov_b32_e32 v142, v180
	v_mov_b32_e32 v143, v181
	v_mov_b32_e32 v144, v182
	v_mov_b32_e32 v145, v183
	s_mov_b64 s[100:101], 0x90000
	v_lshl_add_u64 v[164:165], v[162:163], 0, s[100:101]
	global_load_dwordx4 v[168:171], v[164:165], off
	global_load_dwordx4 v[172:175], v[164:165], off offset:16
	global_load_dwordx4 v[176:179], v[164:165], off offset:512
	global_load_dwordx4 v[180:183], v[164:165], off offset:528
	v_pk_add_f32 v[106:107], v[106:107], v[116:117]
	v_pk_add_f32 v[104:105], v[104:105], v[114:115]
	s_nop 0
	v_pk_add_f32 v[110:111], v[110:111], v[120:121]
	s_nop 0
	v_pk_add_f32 v[116:117], v[96:97], v[142:143]
	v_cvt_pk_bf16_f32 v96, v104, v105
	v_cvt_pk_bf16_f32 v97, v106, v107
	v_pk_add_f32 v[108:109], v[108:109], v[118:119]
	v_pk_add_f32 v[114:115], v[98:99], v[144:145]
	v_cvt_pk_bf16_f32 v98, v108, v109
	v_cvt_pk_bf16_f32 v99, v110, v111
	global_store_dwordx4 v[126:127], v[96:99], off nt
	v_lshlrev_b32_e32 v104, 16, v96
	v_lshlrev_b32_e32 v105, 16, v97
	v_and_b32_e32 v96, 0xffff0000, v96
	v_and_b32_e32 v97, 0xffff0000, v97
	v_pk_add_f32 v[102:103], v[102:103], v[124:125]
	v_and_b32_e32 v107, 0xffff0000, v98
	v_mul_f32_e32 v96, v96, v96
	v_mul_f32_e32 v97, v97, v97
	v_pk_add_f32 v[100:101], v[100:101], v[122:123]
	v_lshlrev_b32_e32 v106, 16, v98
	v_lshlrev_b32_e32 v108, 16, v99
	v_and_b32_e32 v109, 0xffff0000, v99
	v_cvt_pk_bf16_f32 v98, v100, v101
	v_cvt_pk_bf16_f32 v99, v102, v103
	v_mul_f32_e32 v102, v107, v107
	v_fmac_f32_e32 v96, v104, v104
	v_fmac_f32_e32 v97, v105, v105
	v_mul_f32_e32 v103, v109, v109
	v_and_b32_e32 v109, 0xffff0000, v98
	v_fmac_f32_e32 v102, v106, v106
	v_add_f32_e32 v96, v96, v97
	v_lshlrev_b32_e32 v107, 16, v98
	v_and_b32_e32 v111, 0xffff0000, v99
	v_fmac_f32_e32 v103, v108, v108
	v_mul_f32_e32 v104, v109, v109
	v_add_f32_e32 v96, v96, v102
	v_cvt_pk_bf16_f32 v100, v116, v117
	v_cvt_pk_bf16_f32 v101, v114, v115
	v_lshlrev_b32_e32 v110, 16, v99
	v_and_b32_e32 v115, 0xffff0000, v100
	v_mul_f32_e32 v105, v111, v111
	v_fmac_f32_e32 v104, v107, v107
	v_add_f32_e32 v96, v96, v103
	v_lshlrev_b32_e32 v114, 16, v100
	v_and_b32_e32 v117, 0xffff0000, v101
	v_mul_f32_e32 v106, v115, v115
	v_fmac_f32_e32 v105, v110, v110
	v_add_f32_e32 v96, v96, v104
	v_lshlrev_b32_e32 v116, 16, v101
	v_mul_f32_e32 v108, v117, v117
	v_fmac_f32_e32 v106, v114, v114
	v_add_f32_e32 v96, v96, v105
	v_add_f32_e32 v96, v96, v106
	v_fmac_f32_e32 v108, v116, v116
	v_add_f32_e32 v96, v96, v108
	ds_bpermute_b32 v97, v158, v96
	global_store_dwordx4 v[126:127], v[98:101], off offset:256 nt
	s_waitcnt lgkmcnt(0)
	v_add_f32_e32 v96, v96, v97
	ds_bpermute_b32 v97, v159, v96
	s_mov_b64 s[8:9], exec
	s_and_b64 s[4:5], s[8:9], vcc
	v_mov_b32_e32 v198, v246
	v_mov_b32_e32 v199, v247
	v_mov_b32_e32 v205, v249
	v_mov_b32_e32 v196, v251
	v_mov_b32_e32 v251, 0x260
	s_mov_b64 exec, s[4:5]
	s_cbranch_execz .LBB0_463
	v_lshlrev_b64 v[98:99], 6, v[112:113]
	v_lshl_add_u64 v[98:99], s[66:67], 0, v[98:99]
	v_lshl_add_u64 v[98:99], s[6:7], 2, v[98:99]
	s_lshl_b32 s38, s10, 2
	v_lshl_add_u64 v[98:99], v[98:99], 0, s[38:39]
	s_waitcnt lgkmcnt(0)
	v_add_f32_e32 v96, v96, v97
	global_store_dword v[98:99], v96, off
.LBB0_463:
	s_or_b64 exec, exec, s[8:9]
	v_or_b32_e32 v96, 32, v136
	s_waitcnt lgkmcnt(0)
	v_ashrrev_i32_e32 v97, 31, v96
	v_lshlrev_b64 v[98:99], 12, v[96:97]
	v_lshl_add_u64 v[98:99], s[44:45], 0, v[98:99]
	v_lshl_add_u64 v[110:111], v[134:135], 2, v[98:99]
	s_nop 0
	v_lshlrev_b64 v[114:115], 11, v[96:97]
	v_lshl_add_u64 v[114:115], s[68:69], 0, v[114:115]
	v_lshl_add_u64 v[114:115], v[134:135], 1, v[114:115]
	s_waitcnt vmcnt(18)
	v_mov_b32_e32 v98, v184
	v_mov_b32_e32 v99, v185
	v_mov_b32_e32 v100, v186
	v_mov_b32_e32 v101, v187
	v_mov_b32_e32 v102, v188
	v_mov_b32_e32 v103, v189
	v_mov_b32_e32 v104, v190
	v_mov_b32_e32 v105, v191
	v_mov_b32_e32 v106, v192
	v_mov_b32_e32 v107, v193
	v_mov_b32_e32 v108, v194
	v_mov_b32_e32 v109, v195
	v_mov_b32_e32 v110, v208
	v_mov_b32_e32 v111, v209
	v_mov_b32_e32 v112, v210
	v_mov_b32_e32 v113, v211
	s_mov_b64 s[100:101], 0xa0000
	v_lshl_add_u64 v[164:165], v[162:163], 0, s[100:101]
	global_load_dwordx4 v[184:187], v[164:165], off
	global_load_dwordx4 v[188:191], v[164:165], off offset:16
	global_load_dwordx4 v[192:195], v[164:165], off offset:512
	global_load_dwordx4 v[208:211], v[164:165], off offset:528
	v_pk_add_f32 v[90:91], v[90:91], v[100:101]
	v_pk_add_f32 v[88:89], v[88:89], v[98:99]
	s_nop 0
	v_pk_add_f32 v[94:95], v[94:95], v[104:105]
	s_nop 0
	v_pk_add_f32 v[100:101], v[80:81], v[110:111]
	v_cvt_pk_bf16_f32 v80, v88, v89
	v_cvt_pk_bf16_f32 v81, v90, v91
	v_pk_add_f32 v[92:93], v[92:93], v[102:103]
	v_pk_add_f32 v[98:99], v[82:83], v[112:113]
	v_cvt_pk_bf16_f32 v82, v92, v93
	v_cvt_pk_bf16_f32 v83, v94, v95
	global_store_dwordx4 v[114:115], v[80:83], off nt
	v_lshlrev_b32_e32 v88, 16, v80
	v_lshlrev_b32_e32 v89, 16, v81
	v_and_b32_e32 v80, 0xffff0000, v80
	v_and_b32_e32 v81, 0xffff0000, v81
	v_pk_add_f32 v[86:87], v[86:87], v[108:109]
	v_and_b32_e32 v91, 0xffff0000, v82
	v_mul_f32_e32 v80, v80, v80
	v_mul_f32_e32 v81, v81, v81
	v_pk_add_f32 v[84:85], v[84:85], v[106:107]
	v_lshlrev_b32_e32 v90, 16, v82
	v_lshlrev_b32_e32 v92, 16, v83
	v_and_b32_e32 v93, 0xffff0000, v83
	v_cvt_pk_bf16_f32 v82, v84, v85
	v_cvt_pk_bf16_f32 v83, v86, v87
	v_mul_f32_e32 v86, v91, v91
	v_fmac_f32_e32 v80, v88, v88
	v_fmac_f32_e32 v81, v89, v89
	v_mul_f32_e32 v87, v93, v93
	v_and_b32_e32 v93, 0xffff0000, v82
	v_fmac_f32_e32 v86, v90, v90
	v_add_f32_e32 v80, v80, v81
	v_lshlrev_b32_e32 v91, 16, v82
	v_and_b32_e32 v95, 0xffff0000, v83
	v_fmac_f32_e32 v87, v92, v92
	v_mul_f32_e32 v88, v93, v93
	v_add_f32_e32 v80, v80, v86
	v_cvt_pk_bf16_f32 v84, v100, v101
	v_cvt_pk_bf16_f32 v85, v98, v99
	v_lshlrev_b32_e32 v94, 16, v83
	v_and_b32_e32 v99, 0xffff0000, v84
	v_mul_f32_e32 v89, v95, v95
	v_fmac_f32_e32 v88, v91, v91
	v_add_f32_e32 v80, v80, v87
	v_lshlrev_b32_e32 v98, 16, v84
	v_and_b32_e32 v101, 0xffff0000, v85
	v_mul_f32_e32 v90, v99, v99
	v_fmac_f32_e32 v89, v94, v94
	v_add_f32_e32 v80, v80, v88
	v_lshlrev_b32_e32 v100, 16, v85
	v_mul_f32_e32 v92, v101, v101
	v_fmac_f32_e32 v90, v98, v98
	v_add_f32_e32 v80, v80, v89
	v_add_f32_e32 v80, v80, v90
	v_fmac_f32_e32 v92, v100, v100
	v_add_f32_e32 v80, v80, v92
	ds_bpermute_b32 v81, v158, v80
	global_store_dwordx4 v[114:115], v[82:85], off offset:256 nt
	s_waitcnt lgkmcnt(0)
	v_add_f32_e32 v80, v80, v81
	ds_bpermute_b32 v81, v159, v80
	s_and_saveexec_b64 s[8:9], vcc
	s_cbranch_execz .LBB0_465
	v_lshlrev_b64 v[82:83], 6, v[96:97]
	v_lshl_add_u64 v[82:83], s[66:67], 0, v[82:83]
	v_lshl_add_u64 v[82:83], s[6:7], 2, v[82:83]
	s_lshl_b32 s38, s10, 2
	v_lshl_add_u64 v[82:83], v[82:83], 0, s[38:39]
	s_waitcnt lgkmcnt(0)
	v_add_f32_e32 v80, v80, v81
	global_store_dword v[82:83], v80, off
.LBB0_465:
	s_or_b64 exec, exec, s[8:9]
	v_or_b32_e32 v80, 48, v136
	s_waitcnt lgkmcnt(0)
	v_ashrrev_i32_e32 v81, 31, v80
	v_lshlrev_b64 v[82:83], 12, v[80:81]
	v_lshl_add_u64 v[82:83], s[44:45], 0, v[82:83]
	v_lshl_add_u64 v[94:95], v[134:135], 2, v[82:83]
	s_nop 0
	v_lshlrev_b64 v[98:99], 11, v[80:81]
	v_lshl_add_u64 v[98:99], s[68:69], 0, v[98:99]
	v_lshl_add_u64 v[98:99], v[134:135], 1, v[98:99]
	s_waitcnt vmcnt(21)
	v_mov_b32_e32 v82, v212
	v_mov_b32_e32 v83, v213
	v_mov_b32_e32 v84, v214
	v_mov_b32_e32 v85, v215
	v_mov_b32_e32 v86, v216
	v_mov_b32_e32 v87, v217
	v_mov_b32_e32 v88, v218
	v_mov_b32_e32 v89, v219
	v_mov_b32_e32 v90, v220
	v_mov_b32_e32 v91, v221
	v_mov_b32_e32 v92, v222
	v_mov_b32_e32 v93, v223
	v_mov_b32_e32 v94, v224
	v_mov_b32_e32 v95, v225
	v_mov_b32_e32 v96, v226
	v_mov_b32_e32 v97, v227
	s_mov_b64 s[100:101], 0xb0000
	v_lshl_add_u64 v[164:165], v[162:163], 0, s[100:101]
	global_load_dwordx4 v[212:215], v[164:165], off
	global_load_dwordx4 v[216:219], v[164:165], off offset:16
	global_load_dwordx4 v[220:223], v[164:165], off offset:512
	global_load_dwordx4 v[224:227], v[164:165], off offset:528
	v_pk_add_f32 v[74:75], v[74:75], v[84:85]
	v_pk_add_f32 v[72:73], v[72:73], v[82:83]
	s_nop 0
	v_pk_add_f32 v[78:79], v[78:79], v[88:89]
	s_nop 0
	v_pk_add_f32 v[84:85], v[64:65], v[94:95]
	v_cvt_pk_bf16_f32 v64, v72, v73
	v_cvt_pk_bf16_f32 v65, v74, v75
	v_pk_add_f32 v[76:77], v[76:77], v[86:87]
	v_pk_add_f32 v[82:83], v[66:67], v[96:97]
	v_cvt_pk_bf16_f32 v66, v76, v77
	v_cvt_pk_bf16_f32 v67, v78, v79
	global_store_dwordx4 v[98:99], v[64:67], off nt
	v_lshlrev_b32_e32 v72, 16, v64
	v_lshlrev_b32_e32 v73, 16, v65
	v_and_b32_e32 v64, 0xffff0000, v64
	v_and_b32_e32 v65, 0xffff0000, v65
	v_pk_add_f32 v[70:71], v[70:71], v[92:93]
	v_and_b32_e32 v75, 0xffff0000, v66
	v_mul_f32_e32 v64, v64, v64
	v_mul_f32_e32 v65, v65, v65
	v_pk_add_f32 v[68:69], v[68:69], v[90:91]
	v_lshlrev_b32_e32 v74, 16, v66
	v_lshlrev_b32_e32 v76, 16, v67
	v_and_b32_e32 v77, 0xffff0000, v67
	v_cvt_pk_bf16_f32 v66, v68, v69
	v_cvt_pk_bf16_f32 v67, v70, v71
	v_mul_f32_e32 v70, v75, v75
	v_fmac_f32_e32 v64, v72, v72
	v_fmac_f32_e32 v65, v73, v73
	v_mul_f32_e32 v71, v77, v77
	v_and_b32_e32 v77, 0xffff0000, v66
	v_fmac_f32_e32 v70, v74, v74
	v_add_f32_e32 v64, v64, v65
	v_lshlrev_b32_e32 v75, 16, v66
	v_and_b32_e32 v79, 0xffff0000, v67
	v_fmac_f32_e32 v71, v76, v76
	v_mul_f32_e32 v72, v77, v77
	v_add_f32_e32 v64, v64, v70
	v_cvt_pk_bf16_f32 v68, v84, v85
	v_cvt_pk_bf16_f32 v69, v82, v83
	v_lshlrev_b32_e32 v78, 16, v67
	v_and_b32_e32 v83, 0xffff0000, v68
	v_mul_f32_e32 v73, v79, v79
	v_fmac_f32_e32 v72, v75, v75
	v_add_f32_e32 v64, v64, v71
	v_lshlrev_b32_e32 v82, 16, v68
	v_and_b32_e32 v85, 0xffff0000, v69
	v_mul_f32_e32 v74, v83, v83
	v_fmac_f32_e32 v73, v78, v78
	v_add_f32_e32 v64, v64, v72
	v_lshlrev_b32_e32 v84, 16, v69
	v_mul_f32_e32 v76, v85, v85
	v_fmac_f32_e32 v74, v82, v82
	v_add_f32_e32 v64, v64, v73
	v_add_f32_e32 v64, v64, v74
	v_fmac_f32_e32 v76, v84, v84
	v_add_f32_e32 v64, v64, v76
	ds_bpermute_b32 v65, v158, v64
	global_store_dwordx4 v[98:99], v[66:69], off offset:256 nt
	s_waitcnt lgkmcnt(0)
	v_add_f32_e32 v64, v64, v65
	ds_bpermute_b32 v65, v159, v64
	s_and_saveexec_b64 s[8:9], vcc
	s_cbranch_execz .LBB0_467
	v_lshlrev_b64 v[66:67], 6, v[80:81]
	v_lshl_add_u64 v[66:67], s[66:67], 0, v[66:67]
	v_lshl_add_u64 v[66:67], s[6:7], 2, v[66:67]
	s_lshl_b32 s38, s10, 2
	v_lshl_add_u64 v[66:67], v[66:67], 0, s[38:39]
	s_waitcnt lgkmcnt(0)
	v_add_f32_e32 v64, v64, v65
	global_store_dword v[66:67], v64, off
.LBB0_467:
	s_or_b64 exec, exec, s[8:9]
	v_add_u32_e32 v64, 0x80, v136
	s_waitcnt lgkmcnt(0)
	v_ashrrev_i32_e32 v65, 31, v64
	v_lshlrev_b64 v[66:67], 12, v[64:65]
	v_lshl_add_u64 v[66:67], s[44:45], 0, v[66:67]
	v_lshl_add_u64 v[78:79], v[134:135], 2, v[66:67]
	s_nop 0
	v_lshlrev_b64 v[82:83], 11, v[64:65]
	v_lshl_add_u64 v[82:83], s[68:69], 0, v[82:83]
	v_lshl_add_u64 v[82:83], v[134:135], 1, v[82:83]
	s_waitcnt vmcnt(24)
	v_mov_b32_e32 v66, v228
	v_mov_b32_e32 v67, v229
	v_mov_b32_e32 v68, v230
	v_mov_b32_e32 v69, v231
	v_mov_b32_e32 v70, v232
	v_mov_b32_e32 v71, v233
	v_mov_b32_e32 v72, v234
	v_mov_b32_e32 v73, v235
	v_mov_b32_e32 v74, v236
	v_mov_b32_e32 v75, v237
	v_mov_b32_e32 v76, v238
	v_mov_b32_e32 v77, v239
	v_mov_b32_e32 v78, v240
	v_mov_b32_e32 v79, v241
	v_mov_b32_e32 v80, v242
	v_mov_b32_e32 v81, v243
	v_pk_add_f32 v[58:59], v[58:59], v[68:69]
	v_pk_add_f32 v[56:57], v[56:57], v[66:67]
	s_nop 0
	v_pk_add_f32 v[62:63], v[62:63], v[72:73]
	s_nop 0
	v_pk_add_f32 v[68:69], v[48:49], v[78:79]
	v_cvt_pk_bf16_f32 v48, v56, v57
	v_cvt_pk_bf16_f32 v49, v58, v59
	v_pk_add_f32 v[60:61], v[60:61], v[70:71]
	v_pk_add_f32 v[66:67], v[50:51], v[80:81]
	v_cvt_pk_bf16_f32 v50, v60, v61
	v_cvt_pk_bf16_f32 v51, v62, v63
	global_store_dwordx4 v[82:83], v[48:51], off nt
	v_lshlrev_b32_e32 v56, 16, v48
	v_lshlrev_b32_e32 v57, 16, v49
	v_and_b32_e32 v48, 0xffff0000, v48
	v_and_b32_e32 v49, 0xffff0000, v49
	v_pk_add_f32 v[54:55], v[54:55], v[76:77]
	v_and_b32_e32 v59, 0xffff0000, v50
	v_mul_f32_e32 v48, v48, v48
	v_mul_f32_e32 v49, v49, v49
	v_pk_add_f32 v[52:53], v[52:53], v[74:75]
	v_lshlrev_b32_e32 v58, 16, v50
	v_lshlrev_b32_e32 v60, 16, v51
	v_and_b32_e32 v61, 0xffff0000, v51
	v_cvt_pk_bf16_f32 v50, v52, v53
	v_cvt_pk_bf16_f32 v51, v54, v55
	v_mul_f32_e32 v54, v59, v59
	v_fmac_f32_e32 v48, v56, v56
	v_fmac_f32_e32 v49, v57, v57
	v_mul_f32_e32 v55, v61, v61
	v_and_b32_e32 v61, 0xffff0000, v50
	v_fmac_f32_e32 v54, v58, v58
	v_add_f32_e32 v48, v48, v49
	v_lshlrev_b32_e32 v59, 16, v50
	v_and_b32_e32 v63, 0xffff0000, v51
	v_fmac_f32_e32 v55, v60, v60
	v_mul_f32_e32 v56, v61, v61
	v_add_f32_e32 v48, v48, v54
	v_cvt_pk_bf16_f32 v52, v68, v69
	v_cvt_pk_bf16_f32 v53, v66, v67
	v_lshlrev_b32_e32 v62, 16, v51
	v_and_b32_e32 v67, 0xffff0000, v52
	v_mul_f32_e32 v57, v63, v63
	v_fmac_f32_e32 v56, v59, v59
	v_add_f32_e32 v48, v48, v55
	v_lshlrev_b32_e32 v66, 16, v52
	v_and_b32_e32 v69, 0xffff0000, v53
	v_mul_f32_e32 v58, v67, v67
	v_fmac_f32_e32 v57, v62, v62
	v_add_f32_e32 v48, v48, v56
	v_lshlrev_b32_e32 v68, 16, v53
	v_mul_f32_e32 v60, v69, v69
	v_fmac_f32_e32 v58, v66, v66
	v_add_f32_e32 v48, v48, v57
	v_add_f32_e32 v48, v48, v58
	v_fmac_f32_e32 v60, v68, v68
	v_add_f32_e32 v48, v48, v60
	ds_bpermute_b32 v49, v158, v48
	global_store_dwordx4 v[82:83], v[50:53], off offset:256 nt
	s_waitcnt lgkmcnt(0)
	v_add_f32_e32 v48, v48, v49
	ds_bpermute_b32 v49, v159, v48
	s_and_saveexec_b64 s[8:9], vcc
	s_cbranch_execz .LBB0_469
	v_lshlrev_b64 v[50:51], 6, v[64:65]
	v_lshl_add_u64 v[50:51], s[66:67], 0, v[50:51]
	v_lshl_add_u64 v[50:51], s[6:7], 2, v[50:51]
	s_lshl_b32 s38, s10, 2
	v_lshl_add_u64 v[50:51], v[50:51], 0, s[38:39]
	s_waitcnt lgkmcnt(0)
	v_add_f32_e32 v48, v48, v49
	global_store_dword v[50:51], v48, off
.LBB0_469:
	s_or_b64 exec, exec, s[8:9]
	v_add_u32_e32 v48, 0x90, v136
	s_waitcnt lgkmcnt(0)
	v_ashrrev_i32_e32 v49, 31, v48
	v_lshlrev_b64 v[50:51], 12, v[48:49]
	v_lshl_add_u64 v[50:51], s[44:45], 0, v[50:51]
	v_lshl_add_u64 v[62:63], v[134:135], 2, v[50:51]
	s_nop 0
	v_lshlrev_b64 v[66:67], 11, v[48:49]
	v_lshl_add_u64 v[66:67], s[68:69], 0, v[66:67]
	v_lshl_add_u64 v[66:67], v[134:135], 1, v[66:67]
	s_waitcnt vmcnt(20)
	v_mov_b32_e32 v50, v168
	v_mov_b32_e32 v51, v169
	v_mov_b32_e32 v52, v170
	v_mov_b32_e32 v53, v171
	v_mov_b32_e32 v54, v172
	v_mov_b32_e32 v55, v173
	v_mov_b32_e32 v56, v174
	v_mov_b32_e32 v57, v175
	v_mov_b32_e32 v58, v176
	v_mov_b32_e32 v59, v177
	v_mov_b32_e32 v60, v178
	v_mov_b32_e32 v61, v179
	v_mov_b32_e32 v62, v180
	v_mov_b32_e32 v63, v181
	v_mov_b32_e32 v64, v182
	v_mov_b32_e32 v65, v183
	v_pk_add_f32 v[42:43], v[42:43], v[52:53]
	v_pk_add_f32 v[40:41], v[40:41], v[50:51]
	s_nop 0
	v_pk_add_f32 v[46:47], v[46:47], v[56:57]
	s_nop 0
	v_pk_add_f32 v[52:53], v[32:33], v[62:63]
	v_cvt_pk_bf16_f32 v32, v40, v41
	v_cvt_pk_bf16_f32 v33, v42, v43
	v_pk_add_f32 v[44:45], v[44:45], v[54:55]
	v_pk_add_f32 v[50:51], v[34:35], v[64:65]
	v_cvt_pk_bf16_f32 v34, v44, v45
	v_cvt_pk_bf16_f32 v35, v46, v47
	global_store_dwordx4 v[66:67], v[32:35], off nt
	v_lshlrev_b32_e32 v40, 16, v32
	v_lshlrev_b32_e32 v41, 16, v33
	v_and_b32_e32 v32, 0xffff0000, v32
	v_and_b32_e32 v33, 0xffff0000, v33
	v_pk_add_f32 v[38:39], v[38:39], v[60:61]
	v_and_b32_e32 v43, 0xffff0000, v34
	v_mul_f32_e32 v32, v32, v32
	v_mul_f32_e32 v33, v33, v33
	v_pk_add_f32 v[36:37], v[36:37], v[58:59]
	v_lshlrev_b32_e32 v42, 16, v34
	v_lshlrev_b32_e32 v44, 16, v35
	v_and_b32_e32 v45, 0xffff0000, v35
	v_cvt_pk_bf16_f32 v34, v36, v37
	v_cvt_pk_bf16_f32 v35, v38, v39
	v_mul_f32_e32 v38, v43, v43
	v_fmac_f32_e32 v32, v40, v40
	v_fmac_f32_e32 v33, v41, v41
	v_mul_f32_e32 v39, v45, v45
	v_and_b32_e32 v45, 0xffff0000, v34
	v_fmac_f32_e32 v38, v42, v42
	v_add_f32_e32 v32, v32, v33
	v_lshlrev_b32_e32 v43, 16, v34
	v_and_b32_e32 v47, 0xffff0000, v35
	v_fmac_f32_e32 v39, v44, v44
	v_mul_f32_e32 v40, v45, v45
	v_add_f32_e32 v32, v32, v38
	v_cvt_pk_bf16_f32 v36, v52, v53
	v_cvt_pk_bf16_f32 v37, v50, v51
	v_lshlrev_b32_e32 v46, 16, v35
	v_and_b32_e32 v51, 0xffff0000, v36
	v_mul_f32_e32 v41, v47, v47
	v_fmac_f32_e32 v40, v43, v43
	v_add_f32_e32 v32, v32, v39
	v_lshlrev_b32_e32 v50, 16, v36
	v_and_b32_e32 v53, 0xffff0000, v37
	v_mul_f32_e32 v42, v51, v51
	v_fmac_f32_e32 v41, v46, v46
	v_add_f32_e32 v32, v32, v40
	v_lshlrev_b32_e32 v52, 16, v37
	v_mul_f32_e32 v44, v53, v53
	v_fmac_f32_e32 v42, v50, v50
	v_add_f32_e32 v32, v32, v41
	v_add_f32_e32 v32, v32, v42
	v_fmac_f32_e32 v44, v52, v52
	v_add_f32_e32 v32, v32, v44
	ds_bpermute_b32 v33, v158, v32
	global_store_dwordx4 v[66:67], v[34:37], off offset:256 nt
	s_waitcnt lgkmcnt(0)
	v_add_f32_e32 v32, v32, v33
	ds_bpermute_b32 v33, v159, v32
	s_and_saveexec_b64 s[8:9], vcc
	s_cbranch_execz .LBB0_471
	v_lshlrev_b64 v[34:35], 6, v[48:49]
	v_lshl_add_u64 v[34:35], s[66:67], 0, v[34:35]
	v_lshl_add_u64 v[34:35], s[6:7], 2, v[34:35]
	s_lshl_b32 s38, s10, 2
	v_lshl_add_u64 v[34:35], v[34:35], 0, s[38:39]
	s_waitcnt lgkmcnt(0)
	v_add_f32_e32 v32, v32, v33
	global_store_dword v[34:35], v32, off
.LBB0_471:
	s_or_b64 exec, exec, s[8:9]
	v_add_u32_e32 v32, 0xa0, v136
	s_waitcnt lgkmcnt(0)
	v_ashrrev_i32_e32 v33, 31, v32
	v_lshlrev_b64 v[34:35], 12, v[32:33]
	v_lshl_add_u64 v[34:35], s[44:45], 0, v[34:35]
	v_lshl_add_u64 v[46:47], v[134:135], 2, v[34:35]
	s_nop 0
	v_lshlrev_b64 v[50:51], 11, v[32:33]
	v_lshl_add_u64 v[50:51], s[68:69], 0, v[50:51]
	v_lshl_add_u64 v[50:51], v[134:135], 1, v[50:51]
	s_waitcnt vmcnt(16)
	v_mov_b32_e32 v34, v184
	v_mov_b32_e32 v35, v185
	v_mov_b32_e32 v36, v186
	v_mov_b32_e32 v37, v187
	v_mov_b32_e32 v38, v188
	v_mov_b32_e32 v39, v189
	v_mov_b32_e32 v40, v190
	v_mov_b32_e32 v41, v191
	v_mov_b32_e32 v42, v192
	v_mov_b32_e32 v43, v193
	v_mov_b32_e32 v44, v194
	v_mov_b32_e32 v45, v195
	v_mov_b32_e32 v46, v208
	v_mov_b32_e32 v47, v209
	v_mov_b32_e32 v48, v210
	v_mov_b32_e32 v49, v211
	v_pk_add_f32 v[26:27], v[26:27], v[36:37]
	v_pk_add_f32 v[24:25], v[24:25], v[34:35]
	s_nop 0
	v_pk_add_f32 v[30:31], v[30:31], v[40:41]
	s_nop 0
	v_pk_add_f32 v[36:37], v[16:17], v[46:47]
	v_cvt_pk_bf16_f32 v16, v24, v25
	v_cvt_pk_bf16_f32 v17, v26, v27
	v_pk_add_f32 v[28:29], v[28:29], v[38:39]
	v_pk_add_f32 v[34:35], v[18:19], v[48:49]
	v_cvt_pk_bf16_f32 v18, v28, v29
	v_cvt_pk_bf16_f32 v19, v30, v31
	global_store_dwordx4 v[50:51], v[16:19], off nt
	v_lshlrev_b32_e32 v24, 16, v16
	v_lshlrev_b32_e32 v25, 16, v17
	v_and_b32_e32 v16, 0xffff0000, v16
	v_and_b32_e32 v17, 0xffff0000, v17
	v_pk_add_f32 v[22:23], v[22:23], v[44:45]
	v_and_b32_e32 v27, 0xffff0000, v18
	v_mul_f32_e32 v16, v16, v16
	v_mul_f32_e32 v17, v17, v17
	v_pk_add_f32 v[20:21], v[20:21], v[42:43]
	v_lshlrev_b32_e32 v26, 16, v18
	v_lshlrev_b32_e32 v28, 16, v19
	v_and_b32_e32 v29, 0xffff0000, v19
	v_cvt_pk_bf16_f32 v18, v20, v21
	v_cvt_pk_bf16_f32 v19, v22, v23
	v_mul_f32_e32 v22, v27, v27
	v_fmac_f32_e32 v16, v24, v24
	v_fmac_f32_e32 v17, v25, v25
	v_mul_f32_e32 v23, v29, v29
	v_and_b32_e32 v29, 0xffff0000, v18
	v_fmac_f32_e32 v22, v26, v26
	v_add_f32_e32 v16, v16, v17
	v_lshlrev_b32_e32 v27, 16, v18
	v_and_b32_e32 v31, 0xffff0000, v19
	v_fmac_f32_e32 v23, v28, v28
	v_mul_f32_e32 v24, v29, v29
	v_add_f32_e32 v16, v16, v22
	v_cvt_pk_bf16_f32 v20, v36, v37
	v_cvt_pk_bf16_f32 v21, v34, v35
	v_lshlrev_b32_e32 v30, 16, v19
	v_and_b32_e32 v35, 0xffff0000, v20
	v_mul_f32_e32 v25, v31, v31
	v_fmac_f32_e32 v24, v27, v27
	v_add_f32_e32 v16, v16, v23
	v_lshlrev_b32_e32 v34, 16, v20
	v_and_b32_e32 v37, 0xffff0000, v21
	v_mul_f32_e32 v26, v35, v35
	v_fmac_f32_e32 v25, v30, v30
	v_add_f32_e32 v16, v16, v24
	v_lshlrev_b32_e32 v36, 16, v21
	v_mul_f32_e32 v28, v37, v37
	v_fmac_f32_e32 v26, v34, v34
	v_add_f32_e32 v16, v16, v25
	v_add_f32_e32 v16, v16, v26
	v_fmac_f32_e32 v28, v36, v36
	v_add_f32_e32 v16, v16, v28
	ds_bpermute_b32 v17, v158, v16
	global_store_dwordx4 v[50:51], v[18:21], off offset:256 nt
	s_waitcnt lgkmcnt(0)
	v_add_f32_e32 v16, v16, v17
	ds_bpermute_b32 v17, v159, v16
	s_and_saveexec_b64 s[8:9], vcc
	s_cbranch_execz .LBB0_473
	v_lshlrev_b64 v[18:19], 6, v[32:33]
	v_lshl_add_u64 v[18:19], s[66:67], 0, v[18:19]
	v_lshl_add_u64 v[18:19], s[6:7], 2, v[18:19]
	s_lshl_b32 s38, s10, 2
	v_lshl_add_u64 v[18:19], v[18:19], 0, s[38:39]
	s_waitcnt lgkmcnt(0)
	v_add_f32_e32 v16, v16, v17
	global_store_dword v[18:19], v16, off
.LBB0_473:
	s_or_b64 exec, exec, s[8:9]
	v_add_u32_e32 v16, 0xb0, v136
	s_waitcnt lgkmcnt(0)
	v_ashrrev_i32_e32 v17, 31, v16
	v_lshlrev_b64 v[18:19], 12, v[16:17]
	v_lshl_add_u64 v[18:19], s[44:45], 0, v[18:19]
	v_lshl_add_u64 v[30:31], v[134:135], 2, v[18:19]
	s_nop 0
	v_lshlrev_b64 v[34:35], 11, v[16:17]
	v_lshl_add_u64 v[34:35], s[68:69], 0, v[34:35]
	v_lshl_add_u64 v[34:35], v[134:135], 1, v[34:35]
	s_waitcnt vmcnt(12)
	v_mov_b32_e32 v18, v212
	v_mov_b32_e32 v19, v213
	v_mov_b32_e32 v20, v214
	v_mov_b32_e32 v21, v215
	v_mov_b32_e32 v22, v216
	v_mov_b32_e32 v23, v217
	v_mov_b32_e32 v24, v218
	v_mov_b32_e32 v25, v219
	v_mov_b32_e32 v26, v220
	v_mov_b32_e32 v27, v221
	v_mov_b32_e32 v28, v222
	v_mov_b32_e32 v29, v223
	v_mov_b32_e32 v30, v224
	v_mov_b32_e32 v31, v225
	v_mov_b32_e32 v32, v226
	v_mov_b32_e32 v33, v227
	v_pk_add_f32 v[10:11], v[10:11], v[20:21]
	v_pk_add_f32 v[8:9], v[8:9], v[18:19]
	s_nop 0
	v_pk_add_f32 v[14:15], v[14:15], v[24:25]
	s_nop 0
	v_pk_add_f32 v[20:21], v[0:1], v[30:31]
	v_cvt_pk_bf16_f32 v0, v8, v9
	v_cvt_pk_bf16_f32 v1, v10, v11
	v_pk_add_f32 v[12:13], v[12:13], v[22:23]
	v_pk_add_f32 v[18:19], v[2:3], v[32:33]
	v_cvt_pk_bf16_f32 v2, v12, v13
	v_cvt_pk_bf16_f32 v3, v14, v15
	global_store_dwordx4 v[34:35], v[0:3], off nt
	v_lshlrev_b32_e32 v8, 16, v0
	v_lshlrev_b32_e32 v9, 16, v1
	v_and_b32_e32 v0, 0xffff0000, v0
	v_and_b32_e32 v1, 0xffff0000, v1
	v_pk_add_f32 v[6:7], v[6:7], v[28:29]
	v_and_b32_e32 v11, 0xffff0000, v2
	v_mul_f32_e32 v0, v0, v0
	v_mul_f32_e32 v1, v1, v1
	v_pk_add_f32 v[4:5], v[4:5], v[26:27]
	v_lshlrev_b32_e32 v10, 16, v2
	v_lshlrev_b32_e32 v12, 16, v3
	v_and_b32_e32 v13, 0xffff0000, v3
	v_cvt_pk_bf16_f32 v2, v4, v5
	v_cvt_pk_bf16_f32 v3, v6, v7
	v_mul_f32_e32 v6, v11, v11
	v_fmac_f32_e32 v0, v8, v8
	v_fmac_f32_e32 v1, v9, v9
	v_mul_f32_e32 v7, v13, v13
	v_and_b32_e32 v13, 0xffff0000, v2
	v_fmac_f32_e32 v6, v10, v10
	v_add_f32_e32 v0, v0, v1
	v_lshlrev_b32_e32 v11, 16, v2
	v_and_b32_e32 v15, 0xffff0000, v3
	v_fmac_f32_e32 v7, v12, v12
	v_mul_f32_e32 v8, v13, v13
	v_add_f32_e32 v0, v0, v6
	v_cvt_pk_bf16_f32 v4, v20, v21
	v_cvt_pk_bf16_f32 v5, v18, v19
	v_lshlrev_b32_e32 v14, 16, v3
	v_and_b32_e32 v19, 0xffff0000, v4
	v_mul_f32_e32 v9, v15, v15
	v_fmac_f32_e32 v8, v11, v11
	v_add_f32_e32 v0, v0, v7
	v_lshlrev_b32_e32 v18, 16, v4
	v_and_b32_e32 v21, 0xffff0000, v5
	v_mul_f32_e32 v10, v19, v19
	v_fmac_f32_e32 v9, v14, v14
	v_add_f32_e32 v0, v0, v8
	v_lshlrev_b32_e32 v20, 16, v5
	v_mul_f32_e32 v12, v21, v21
	v_fmac_f32_e32 v10, v18, v18
	v_add_f32_e32 v0, v0, v9
	v_add_f32_e32 v0, v0, v10
	v_fmac_f32_e32 v12, v20, v20
	v_add_f32_e32 v0, v0, v12
	ds_bpermute_b32 v1, v158, v0
	global_store_dwordx4 v[34:35], v[2:5], off offset:256 nt
	s_waitcnt lgkmcnt(0)
	v_add_f32_e32 v0, v0, v1
	ds_bpermute_b32 v1, v159, v0
	s_and_saveexec_b64 s[8:9], vcc
	s_cbranch_execz .LBB0_475
	v_lshlrev_b64 v[2:3], 6, v[16:17]
	v_lshl_add_u64 v[2:3], s[66:67], 0, v[2:3]
	v_lshl_add_u64 v[2:3], s[6:7], 2, v[2:3]
	s_lshl_b32 s38, s10, 2
	v_lshl_add_u64 v[2:3], v[2:3], 0, s[38:39]
	s_waitcnt lgkmcnt(0)
	v_add_f32_e32 v0, v0, v1
	global_store_dword v[2:3], v0, off

.LBB0_484:
	s_or_b64 exec, exec, s[10:11]
	s_andn2_b64 vcc, exec, s[74:75]
	s_cbranch_vccnz .LBB0_486
	global_load_dwordx4 v[216:219], v[92:93], off
	global_load_dwordx4 v[220:223], v[94:95], off
	global_load_dwordx4 v[224:227], v[96:97], off
	global_load_dwordx4 v[228:231], v[98:99], off
	global_load_dwordx4 v[232:235], v[100:101], off
	global_load_dwordx4 v[236:239], v[102:103], off
	global_load_dwordx4 v[240:243], v[104:105], off
	global_load_dwordx4 v[244:247], v[106:107], off
	s_waitcnt vmcnt(7)
	v_mov_b32_e32 v0, v216
	v_mov_b32_e32 v1, v217
	v_mov_b32_e32 v2, v218
	v_mov_b32_e32 v3, v219
	v_cndmask_b32_e64 v0, v0, 0, s[42:43]
	v_cndmask_b32_e64 v1, v1, 0, s[42:43]
	v_cndmask_b32_e64 v2, v2, 0, s[42:43]
	v_cndmask_b32_e64 v3, v3, 0, s[42:43]
	v_cvt_pk_bf16_f32 v0, v0, v1
	v_cvt_pk_bf16_f32 v1, v2, v3
	ds_write_b64 v140, v[0:1]
	s_waitcnt vmcnt(6)
	v_mov_b32_e32 v0, v220
	v_mov_b32_e32 v1, v221
	v_mov_b32_e32 v2, v222
	v_mov_b32_e32 v3, v223
	v_cndmask_b32_e64 v0, v0, 0, s[44:45]
	v_cndmask_b32_e64 v1, v1, 0, s[44:45]
	v_cndmask_b32_e64 v2, v2, 0, s[44:45]
	v_cndmask_b32_e64 v3, v3, 0, s[44:45]
	v_cvt_pk_bf16_f32 v0, v0, v1
	v_cvt_pk_bf16_f32 v1, v2, v3
	ds_write_b64 v171, v[0:1]
	s_waitcnt vmcnt(5)
	v_mov_b32_e32 v0, v224
	v_mov_b32_e32 v1, v225
	v_mov_b32_e32 v2, v226
	v_mov_b32_e32 v3, v227
	v_cndmask_b32_e64 v0, v0, 0, s[46:47]
	v_cndmask_b32_e64 v1, v1, 0, s[46:47]
	v_cndmask_b32_e64 v2, v2, 0, s[46:47]
	v_cndmask_b32_e64 v3, v3, 0, s[46:47]
	v_cvt_pk_bf16_f32 v0, v0, v1
	v_cvt_pk_bf16_f32 v1, v2, v3
	ds_write_b64 v172, v[0:1]
	s_waitcnt vmcnt(4)
	v_mov_b32_e32 v0, v228
	v_mov_b32_e32 v1, v229
	v_mov_b32_e32 v2, v230
	v_mov_b32_e32 v3, v231
	v_cndmask_b32_e64 v0, v0, 0, s[48:49]
	v_cndmask_b32_e64 v1, v1, 0, s[48:49]
	v_cndmask_b32_e64 v2, v2, 0, s[48:49]
	v_cndmask_b32_e64 v3, v3, 0, s[48:49]
	v_cvt_pk_bf16_f32 v0, v0, v1
	v_cvt_pk_bf16_f32 v1, v2, v3
	ds_write_b64 v173, v[0:1]
	s_waitcnt vmcnt(3)
	v_mov_b32_e32 v0, v232
	v_mov_b32_e32 v1, v233
	v_mov_b32_e32 v2, v234
	v_mov_b32_e32 v3, v235
	v_cndmask_b32_e64 v0, v0, 0, s[50:51]
	v_cndmask_b32_e64 v1, v1, 0, s[50:51]
	v_cndmask_b32_e64 v2, v2, 0, s[50:51]
	v_cndmask_b32_e64 v3, v3, 0, s[50:51]
	v_cvt_pk_bf16_f32 v0, v0, v1
	v_cvt_pk_bf16_f32 v1, v2, v3
	ds_write_b64 v174, v[0:1]
	s_waitcnt vmcnt(2)
	v_mov_b32_e32 v0, v236
	v_mov_b32_e32 v1, v237
	v_mov_b32_e32 v2, v238
	v_mov_b32_e32 v3, v239
	v_cndmask_b32_e64 v0, v0, 0, s[52:53]
	v_cndmask_b32_e64 v1, v1, 0, s[52:53]
	v_cndmask_b32_e64 v2, v2, 0, s[52:53]
	v_cndmask_b32_e64 v3, v3, 0, s[52:53]
	v_cvt_pk_bf16_f32 v0, v0, v1
	v_cvt_pk_bf16_f32 v1, v2, v3
	ds_write_b64 v175, v[0:1]
	s_waitcnt vmcnt(1)
	v_mov_b32_e32 v0, v240
	v_mov_b32_e32 v1, v241
	v_mov_b32_e32 v2, v242
	v_mov_b32_e32 v3, v243
	v_cndmask_b32_e64 v0, v0, 0, s[54:55]
	v_cndmask_b32_e64 v1, v1, 0, s[54:55]
	v_cndmask_b32_e64 v2, v2, 0, s[54:55]
	v_cndmask_b32_e64 v3, v3, 0, s[54:55]
	v_cvt_pk_bf16_f32 v0, v0, v1
	v_cvt_pk_bf16_f32 v1, v2, v3
	ds_write_b64 v176, v[0:1]
	s_waitcnt vmcnt(0)
	v_mov_b32_e32 v0, v244
	v_mov_b32_e32 v1, v245
	v_mov_b32_e32 v2, v246
	v_mov_b32_e32 v3, v247
	v_cndmask_b32_e64 v0, v0, 0, s[56:57]
	v_cndmask_b32_e64 v1, v1, 0, s[56:57]
	v_cndmask_b32_e64 v2, v2, 0, s[56:57]
	v_cndmask_b32_e64 v3, v3, 0, s[56:57]
	v_cvt_pk_bf16_f32 v0, v0, v1
	v_cvt_pk_bf16_f32 v1, v2, v3
	ds_write_b64 v177, v[0:1]
.LBB0_486:
	s_waitcnt lgkmcnt(0)
	s_barrier
	global_load_dword v197, v[126:127], off
	global_load_dword v200, v[128:129], off offset:64
	global_load_dword v201, v[128:129], off offset:128
	global_load_dword v202, v[128:129], off offset:192
	global_load_dword v203, v[128:129], off offset:256
	global_load_dword v204, v[128:129], off offset:320
	global_load_dword v215, v[128:129], off offset:384
	global_load_dword v249, v[128:129], off offset:448
	global_load_dwordx4 v[0:3], v[108:109], off
	global_load_dwordx4 v[4:7], v[108:109], off offset:16
	global_load_dwordx4 v[8:11], v[110:111], off
	global_load_dwordx4 v[12:15], v[110:111], off offset:16
	s_lshl_b64 s[4:5], s[8:9], 19
	v_lshl_add_u64 v[20:21], v[130:131], 0, s[4:5]
	s_mov_b32 s4, 0
	v_mov_b32_e32 v22, v86
	s_mov_b64 s[100:101], 0x20000
	v_add_co_u32_e32 v24, vcc, 0xffff0000, v20
	s_nop 1
	v_addc_co_u32_e32 v25, vcc, -1, v21, vcc
	v_mov_b32_e32 v26, v20
	v_mov_b32_e32 v27, v21
	global_load_dwordx4 v[216:219], v[24:25], off
	global_load_dwordx4 v[220:223], v[26:27], off
	v_lshl_add_u64 v[24:25], v[24:25], 0, s[100:101]
	v_lshl_add_u64 v[26:27], v[26:27], 0, s[100:101]
	global_load_dwordx4 v[224:227], v[24:25], off
	global_load_dwordx4 v[228:231], v[26:27], off
	v_lshl_add_u64 v[24:25], v[24:25], 0, s[100:101]
	v_lshl_add_u64 v[26:27], v[26:27], 0, s[100:101]
	global_load_dwordx4 v[232:235], v[24:25], off
	global_load_dwordx4 v[236:239], v[26:27], off
	v_lshl_add_u64 v[24:25], v[24:25], 0, s[100:101]
	v_lshl_add_u64 v[26:27], v[26:27], 0, s[100:101]
	global_load_dwordx4 v[240:243], v[24:25], off
	global_load_dwordx4 v[244:247], v[26:27], off
.LBB0_487:
	v_add_co_u32_e32 v16, vcc, 0xffff0000, v20
	v_add_u32_e32 v23, s4, v170
	s_nop 0
	v_addc_co_u32_e32 v17, vcc, -1, v21, vcc
	v_add_u32_e32 v24, 0x19000, v23
	ds_read_b32 v24, v24
	v_add_u32_e32 v25, 0x19200, v23
	ds_read_b32 v25, v25
	v_lshrrev_b32_e32 v26, 3, v22
	v_xor_b32_e32 v26, v26, v168
	v_lshlrev_b32_e32 v26, 4, v26
	v_add_u32_e32 v28, v169, v26
	s_addk_i32 s4, 0x80
	s_mov_b64 s[8:9], 0x20000
	s_waitcnt vmcnt(7)
	v_mov_b32_e32 v16, v216
	v_mov_b32_e32 v17, v217
	v_mov_b32_e32 v18, v218
	v_mov_b32_e32 v19, v219
	v_lshlrev_b32_e32 v27, 16, v16
	s_waitcnt lgkmcnt(1)
	v_sub_f32_e32 v27, v27, v24
	v_and_b32_e32 v16, 0xffff0000, v16
	s_waitcnt lgkmcnt(0)
	v_mul_f32_e32 v27, v25, v27
	v_sub_f32_e32 v16, v16, v24
	v_fma_f32 v27, v0, v27, v8
	v_mul_f32_e32 v16, v25, v16
	v_cvt_pk_bf16_f32 v27, v27, v27
	v_fma_f32 v16, v1, v16, v9
	ds_write_b16 v28, v27 offset:34816
	v_cvt_pk_bf16_f32 v16, v16, v16
	v_xad_u32 v27, v26, 16, v169
	ds_write_b16 v27, v16 offset:35072
	v_lshlrev_b32_e32 v16, 16, v17
	v_sub_f32_e32 v16, v16, v24
	v_mul_f32_e32 v16, v25, v16
	v_fma_f32 v16, v2, v16, v10
	v_cvt_pk_bf16_f32 v16, v16, v16
	v_xad_u32 v27, v26, 32, v169
	ds_write_b16 v27, v16 offset:35328
	v_and_b32_e32 v16, 0xffff0000, v17
	v_sub_f32_e32 v16, v16, v24
	v_mul_f32_e32 v16, v25, v16
	v_fma_f32 v16, v3, v16, v11
	v_cvt_pk_bf16_f32 v16, v16, v16
	v_xad_u32 v17, v26, 48, v169
	ds_write_b16 v17, v16 offset:35584
	v_lshlrev_b32_e32 v16, 16, v18
	v_sub_f32_e32 v16, v16, v24
	v_mul_f32_e32 v16, v25, v16
	v_fma_f32 v16, v4, v16, v12
	v_cvt_pk_bf16_f32 v16, v16, v16
	v_xad_u32 v17, v26, 64, v169
	ds_write_b16 v17, v16 offset:35840
	v_and_b32_e32 v16, 0xffff0000, v18
	v_sub_f32_e32 v16, v16, v24
	v_mul_f32_e32 v16, v25, v16
	v_fma_f32 v16, v5, v16, v13
	v_cvt_pk_bf16_f32 v16, v16, v16
	v_xad_u32 v17, v26, s20, v169
	ds_write_b16 v17, v16 offset:36096
	v_lshlrev_b32_e32 v16, 16, v19
	v_sub_f32_e32 v16, v16, v24
	v_mul_f32_e32 v16, v25, v16
	v_fma_f32 v16, v6, v16, v14
	v_cvt_pk_bf16_f32 v16, v16, v16
	v_xad_u32 v17, v26, s21, v169
	ds_write_b16 v17, v16 offset:36352
	v_and_b32_e32 v16, 0xffff0000, v19
	v_sub_f32_e32 v16, v16, v24
	v_mul_f32_e32 v16, v25, v16
	v_fma_f32 v16, v7, v16, v15
	v_cvt_pk_bf16_f32 v16, v16, v16
	v_xad_u32 v17, v26, s22, v169
	ds_write_b16 v17, v16 offset:36608
	v_add_u32_e32 v25, 0x19040, v23
	ds_read_b32 v25, v25
	v_add_u32_e32 v23, 0x19240, v23
	ds_read_b32 v23, v23
	v_add_u32_e32 v24, 16, v22
	v_lshrrev_b32_e32 v24, 3, v24
	v_xor_b32_e32 v24, v24, v168
	v_lshlrev_b32_e32 v24, 4, v24
	v_add_u32_e32 v27, v169, v24
	v_add_u32_e32 v22, 32, v22
	v_lshl_add_u64 v[20:21], v[20:21], 0, s[8:9]
	s_waitcnt vmcnt(6)
	v_mov_b32_e32 v16, v220
	v_mov_b32_e32 v17, v221
	v_mov_b32_e32 v18, v222
	v_mov_b32_e32 v19, v223
	v_lshlrev_b32_e32 v26, 16, v16
	s_waitcnt lgkmcnt(1)
	v_sub_f32_e32 v26, v26, v25
	v_and_b32_e32 v16, 0xffff0000, v16
	s_waitcnt lgkmcnt(0)
	v_mul_f32_e32 v26, v23, v26
	v_sub_f32_e32 v16, v16, v25
	v_fma_f32 v26, v0, v26, v8
	v_mul_f32_e32 v16, v23, v16
	v_cvt_pk_bf16_f32 v26, v26, v26
	v_fma_f32 v16, v1, v16, v9
	ds_write_b16 v27, v26 offset:34816
	v_cvt_pk_bf16_f32 v16, v16, v16
	v_xad_u32 v26, v24, 16, v169
	ds_write_b16 v26, v16 offset:35072
	v_lshlrev_b32_e32 v16, 16, v17
	v_sub_f32_e32 v16, v16, v25
	v_mul_f32_e32 v16, v23, v16
	v_fma_f32 v16, v2, v16, v10
	v_cvt_pk_bf16_f32 v16, v16, v16
	v_xad_u32 v26, v24, 32, v169
	ds_write_b16 v26, v16 offset:35328
	v_and_b32_e32 v16, 0xffff0000, v17
	v_sub_f32_e32 v16, v16, v25
	v_mul_f32_e32 v16, v23, v16
	v_fma_f32 v16, v3, v16, v11
	v_cvt_pk_bf16_f32 v16, v16, v16
	v_xad_u32 v17, v24, 48, v169
	ds_write_b16 v17, v16 offset:35584
	v_lshlrev_b32_e32 v16, 16, v18
	v_sub_f32_e32 v16, v16, v25
	v_mul_f32_e32 v16, v23, v16
	v_fma_f32 v16, v4, v16, v12
	v_cvt_pk_bf16_f32 v16, v16, v16
	v_xad_u32 v17, v24, 64, v169
	ds_write_b16 v17, v16 offset:35840
	v_and_b32_e32 v16, 0xffff0000, v18
	v_sub_f32_e32 v16, v16, v25
	v_mul_f32_e32 v16, v23, v16
	v_fma_f32 v16, v5, v16, v13
	v_cvt_pk_bf16_f32 v16, v16, v16
	v_xad_u32 v17, v24, s20, v169
	ds_write_b16 v17, v16 offset:36096
	v_lshlrev_b32_e32 v16, 16, v19
	v_sub_f32_e32 v16, v16, v25
	v_mul_f32_e32 v16, v23, v16
	v_fma_f32 v16, v6, v16, v14
	v_cvt_pk_bf16_f32 v16, v16, v16
	v_xad_u32 v17, v24, s21, v169
	ds_write_b16 v17, v16 offset:36352
	v_and_b32_e32 v16, 0xffff0000, v19
	v_sub_f32_e32 v16, v16, v25
	v_mul_f32_e32 v16, v23, v16
	v_fma_f32 v16, v7, v16, v15
	v_xad_u32 v17, v24, s22, v169
	v_cvt_pk_bf16_f32 v16, v16, v16
	ds_write_b16 v17, v16 offset:36608
	v_add_co_u32_e32 v16, vcc, 0xffff0000, v20
	v_add_u32_e32 v23, s4, v170
	s_nop 0
	v_addc_co_u32_e32 v17, vcc, -1, v21, vcc
	v_add_u32_e32 v24, 0x19000, v23
	ds_read_b32 v24, v24
	v_add_u32_e32 v25, 0x19200, v23
	ds_read_b32 v25, v25
	v_lshrrev_b32_e32 v26, 3, v22
	v_xor_b32_e32 v26, v26, v168
	v_lshlrev_b32_e32 v26, 4, v26
	v_add_u32_e32 v28, v169, v26
	s_addk_i32 s4, 0x80
	s_mov_b64 s[8:9], 0x20000
	s_waitcnt vmcnt(5)
	v_mov_b32_e32 v16, v224
	v_mov_b32_e32 v17, v225
	v_mov_b32_e32 v18, v226
	v_mov_b32_e32 v19, v227
	v_lshlrev_b32_e32 v27, 16, v16
	s_waitcnt lgkmcnt(1)
	v_sub_f32_e32 v27, v27, v24
	v_and_b32_e32 v16, 0xffff0000, v16
	s_waitcnt lgkmcnt(0)
	v_mul_f32_e32 v27, v25, v27
	v_sub_f32_e32 v16, v16, v24
	v_fma_f32 v27, v0, v27, v8
	v_mul_f32_e32 v16, v25, v16
	v_cvt_pk_bf16_f32 v27, v27, v27
	v_fma_f32 v16, v1, v16, v9
	ds_write_b16 v28, v27 offset:34816
	v_cvt_pk_bf16_f32 v16, v16, v16
	v_xad_u32 v27, v26, 16, v169
	ds_write_b16 v27, v16 offset:35072
	v_lshlrev_b32_e32 v16, 16, v17
	v_sub_f32_e32 v16, v16, v24
	v_mul_f32_e32 v16, v25, v16
	v_fma_f32 v16, v2, v16, v10
	v_cvt_pk_bf16_f32 v16, v16, v16
	v_xad_u32 v27, v26, 32, v169
	ds_write_b16 v27, v16 offset:35328
	v_and_b32_e32 v16, 0xffff0000, v17
	v_sub_f32_e32 v16, v16, v24
	v_mul_f32_e32 v16, v25, v16
	v_fma_f32 v16, v3, v16, v11
	v_cvt_pk_bf16_f32 v16, v16, v16
	v_xad_u32 v17, v26, 48, v169
	ds_write_b16 v17, v16 offset:35584
	v_lshlrev_b32_e32 v16, 16, v18
	v_sub_f32_e32 v16, v16, v24
	v_mul_f32_e32 v16, v25, v16
	v_fma_f32 v16, v4, v16, v12
	v_cvt_pk_bf16_f32 v16, v16, v16
	v_xad_u32 v17, v26, 64, v169
	ds_write_b16 v17, v16 offset:35840
	v_and_b32_e32 v16, 0xffff0000, v18
	v_sub_f32_e32 v16, v16, v24
	v_mul_f32_e32 v16, v25, v16
	v_fma_f32 v16, v5, v16, v13
	v_cvt_pk_bf16_f32 v16, v16, v16
	v_xad_u32 v17, v26, s20, v169
	ds_write_b16 v17, v16 offset:36096
	v_lshlrev_b32_e32 v16, 16, v19
	v_sub_f32_e32 v16, v16, v24
	v_mul_f32_e32 v16, v25, v16
	v_fma_f32 v16, v6, v16, v14
	v_cvt_pk_bf16_f32 v16, v16, v16
	v_xad_u32 v17, v26, s21, v169
	ds_write_b16 v17, v16 offset:36352
	v_and_b32_e32 v16, 0xffff0000, v19
	v_sub_f32_e32 v16, v16, v24
	v_mul_f32_e32 v16, v25, v16
	v_fma_f32 v16, v7, v16, v15
	v_cvt_pk_bf16_f32 v16, v16, v16
	v_xad_u32 v17, v26, s22, v169
	ds_write_b16 v17, v16 offset:36608
	v_add_u32_e32 v25, 0x19040, v23
	ds_read_b32 v25, v25
	v_add_u32_e32 v23, 0x19240, v23
	ds_read_b32 v23, v23
	v_add_u32_e32 v24, 16, v22
	v_lshrrev_b32_e32 v24, 3, v24
	v_xor_b32_e32 v24, v24, v168
	v_lshlrev_b32_e32 v24, 4, v24
	v_add_u32_e32 v27, v169, v24
	v_add_u32_e32 v22, 32, v22
	v_lshl_add_u64 v[20:21], v[20:21], 0, s[8:9]
	s_waitcnt vmcnt(4)
	v_mov_b32_e32 v16, v228
	v_mov_b32_e32 v17, v229
	v_mov_b32_e32 v18, v230
	v_mov_b32_e32 v19, v231
	v_lshlrev_b32_e32 v26, 16, v16
	s_waitcnt lgkmcnt(1)
	v_sub_f32_e32 v26, v26, v25
	v_and_b32_e32 v16, 0xffff0000, v16
	s_waitcnt lgkmcnt(0)
	v_mul_f32_e32 v26, v23, v26
	v_sub_f32_e32 v16, v16, v25
	v_fma_f32 v26, v0, v26, v8
	v_mul_f32_e32 v16, v23, v16
	v_cvt_pk_bf16_f32 v26, v26, v26
	v_fma_f32 v16, v1, v16, v9
	ds_write_b16 v27, v26 offset:34816
	v_cvt_pk_bf16_f32 v16, v16, v16
	v_xad_u32 v26, v24, 16, v169
	ds_write_b16 v26, v16 offset:35072
	v_lshlrev_b32_e32 v16, 16, v17
	v_sub_f32_e32 v16, v16, v25
	v_mul_f32_e32 v16, v23, v16
	v_fma_f32 v16, v2, v16, v10
	v_cvt_pk_bf16_f32 v16, v16, v16
	v_xad_u32 v26, v24, 32, v169
	ds_write_b16 v26, v16 offset:35328
	v_and_b32_e32 v16, 0xffff0000, v17
	v_sub_f32_e32 v16, v16, v25
	v_mul_f32_e32 v16, v23, v16
	v_fma_f32 v16, v3, v16, v11
	v_cvt_pk_bf16_f32 v16, v16, v16
	v_xad_u32 v17, v24, 48, v169
	ds_write_b16 v17, v16 offset:35584
	v_lshlrev_b32_e32 v16, 16, v18
	v_sub_f32_e32 v16, v16, v25
	v_mul_f32_e32 v16, v23, v16
	v_fma_f32 v16, v4, v16, v12
	v_cvt_pk_bf16_f32 v16, v16, v16
	v_xad_u32 v17, v24, 64, v169
	ds_write_b16 v17, v16 offset:35840
	v_and_b32_e32 v16, 0xffff0000, v18
	v_sub_f32_e32 v16, v16, v25
	v_mul_f32_e32 v16, v23, v16
	v_fma_f32 v16, v5, v16, v13
	v_cvt_pk_bf16_f32 v16, v16, v16
	v_xad_u32 v17, v24, s20, v169
	ds_write_b16 v17, v16 offset:36096
	v_lshlrev_b32_e32 v16, 16, v19
	v_sub_f32_e32 v16, v16, v25
	v_mul_f32_e32 v16, v23, v16
	v_fma_f32 v16, v6, v16, v14
	v_cvt_pk_bf16_f32 v16, v16, v16
	v_xad_u32 v17, v24, s21, v169
	ds_write_b16 v17, v16 offset:36352
	v_and_b32_e32 v16, 0xffff0000, v19
	v_sub_f32_e32 v16, v16, v25
	v_mul_f32_e32 v16, v23, v16
	v_fma_f32 v16, v7, v16, v15
	v_xad_u32 v17, v24, s22, v169
	v_cvt_pk_bf16_f32 v16, v16, v16
	ds_write_b16 v17, v16 offset:36608
	v_add_co_u32_e32 v16, vcc, 0xffff0000, v20
	v_add_u32_e32 v23, s4, v170
	s_nop 0
	v_addc_co_u32_e32 v17, vcc, -1, v21, vcc
	v_add_u32_e32 v24, 0x19000, v23
	ds_read_b32 v24, v24
	v_add_u32_e32 v25, 0x19200, v23
	ds_read_b32 v25, v25
	v_lshrrev_b32_e32 v26, 3, v22
	v_xor_b32_e32 v26, v26, v168
	v_lshlrev_b32_e32 v26, 4, v26
	v_add_u32_e32 v28, v169, v26
	s_addk_i32 s4, 0x80
	s_mov_b64 s[8:9], 0x20000
	s_waitcnt vmcnt(3)
	v_mov_b32_e32 v16, v232
	v_mov_b32_e32 v17, v233
	v_mov_b32_e32 v18, v234
	v_mov_b32_e32 v19, v235
	v_lshlrev_b32_e32 v27, 16, v16
	s_waitcnt lgkmcnt(1)
	v_sub_f32_e32 v27, v27, v24
	v_and_b32_e32 v16, 0xffff0000, v16
	s_waitcnt lgkmcnt(0)
	v_mul_f32_e32 v27, v25, v27
	v_sub_f32_e32 v16, v16, v24
	v_fma_f32 v27, v0, v27, v8
	v_mul_f32_e32 v16, v25, v16
	v_cvt_pk_bf16_f32 v27, v27, v27
	v_fma_f32 v16, v1, v16, v9
	ds_write_b16 v28, v27 offset:34816
	v_cvt_pk_bf16_f32 v16, v16, v16
	v_xad_u32 v27, v26, 16, v169
	ds_write_b16 v27, v16 offset:35072
	v_lshlrev_b32_e32 v16, 16, v17
	v_sub_f32_e32 v16, v16, v24
	v_mul_f32_e32 v16, v25, v16
	v_fma_f32 v16, v2, v16, v10
	v_cvt_pk_bf16_f32 v16, v16, v16
	v_xad_u32 v27, v26, 32, v169
	ds_write_b16 v27, v16 offset:35328
	v_and_b32_e32 v16, 0xffff0000, v17
	v_sub_f32_e32 v16, v16, v24
	v_mul_f32_e32 v16, v25, v16
	v_fma_f32 v16, v3, v16, v11
	v_cvt_pk_bf16_f32 v16, v16, v16
	v_xad_u32 v17, v26, 48, v169
	ds_write_b16 v17, v16 offset:35584
	v_lshlrev_b32_e32 v16, 16, v18
	v_sub_f32_e32 v16, v16, v24
	v_mul_f32_e32 v16, v25, v16
	v_fma_f32 v16, v4, v16, v12
	v_cvt_pk_bf16_f32 v16, v16, v16
	v_xad_u32 v17, v26, 64, v169
	ds_write_b16 v17, v16 offset:35840
	v_and_b32_e32 v16, 0xffff0000, v18
	v_sub_f32_e32 v16, v16, v24
	v_mul_f32_e32 v16, v25, v16
	v_fma_f32 v16, v5, v16, v13
	v_cvt_pk_bf16_f32 v16, v16, v16
	v_xad_u32 v17, v26, s20, v169
	ds_write_b16 v17, v16 offset:36096
	v_lshlrev_b32_e32 v16, 16, v19
	v_sub_f32_e32 v16, v16, v24
	v_mul_f32_e32 v16, v25, v16
	v_fma_f32 v16, v6, v16, v14
	v_cvt_pk_bf16_f32 v16, v16, v16
	v_xad_u32 v17, v26, s21, v169
	ds_write_b16 v17, v16 offset:36352
	v_and_b32_e32 v16, 0xffff0000, v19
	v_sub_f32_e32 v16, v16, v24
	v_mul_f32_e32 v16, v25, v16
	v_fma_f32 v16, v7, v16, v15
	v_cvt_pk_bf16_f32 v16, v16, v16
	v_xad_u32 v17, v26, s22, v169
	ds_write_b16 v17, v16 offset:36608
	v_add_u32_e32 v25, 0x19040, v23
	ds_read_b32 v25, v25
	v_add_u32_e32 v23, 0x19240, v23
	ds_read_b32 v23, v23
	v_add_u32_e32 v24, 16, v22
	v_lshrrev_b32_e32 v24, 3, v24
	v_xor_b32_e32 v24, v24, v168
	v_lshlrev_b32_e32 v24, 4, v24
	v_add_u32_e32 v27, v169, v24
	v_add_u32_e32 v22, 32, v22
	v_lshl_add_u64 v[20:21], v[20:21], 0, s[8:9]
	s_waitcnt vmcnt(2)
	v_mov_b32_e32 v16, v236
	v_mov_b32_e32 v17, v237
	v_mov_b32_e32 v18, v238
	v_mov_b32_e32 v19, v239
	v_lshlrev_b32_e32 v26, 16, v16
	s_waitcnt lgkmcnt(1)
	v_sub_f32_e32 v26, v26, v25
	v_and_b32_e32 v16, 0xffff0000, v16
	s_waitcnt lgkmcnt(0)
	v_mul_f32_e32 v26, v23, v26
	v_sub_f32_e32 v16, v16, v25
	v_fma_f32 v26, v0, v26, v8
	v_mul_f32_e32 v16, v23, v16
	v_cvt_pk_bf16_f32 v26, v26, v26
	v_fma_f32 v16, v1, v16, v9
	ds_write_b16 v27, v26 offset:34816
	v_cvt_pk_bf16_f32 v16, v16, v16
	v_xad_u32 v26, v24, 16, v169
	ds_write_b16 v26, v16 offset:35072
	v_lshlrev_b32_e32 v16, 16, v17
	v_sub_f32_e32 v16, v16, v25
	v_mul_f32_e32 v16, v23, v16
	v_fma_f32 v16, v2, v16, v10
	v_cvt_pk_bf16_f32 v16, v16, v16
	v_xad_u32 v26, v24, 32, v169
	ds_write_b16 v26, v16 offset:35328
	v_and_b32_e32 v16, 0xffff0000, v17
	v_sub_f32_e32 v16, v16, v25
	v_mul_f32_e32 v16, v23, v16
	v_fma_f32 v16, v3, v16, v11
	v_cvt_pk_bf16_f32 v16, v16, v16
	v_xad_u32 v17, v24, 48, v169
	ds_write_b16 v17, v16 offset:35584
	v_lshlrev_b32_e32 v16, 16, v18
	v_sub_f32_e32 v16, v16, v25
	v_mul_f32_e32 v16, v23, v16
	v_fma_f32 v16, v4, v16, v12
	v_cvt_pk_bf16_f32 v16, v16, v16
	v_xad_u32 v17, v24, 64, v169
	ds_write_b16 v17, v16 offset:35840
	v_and_b32_e32 v16, 0xffff0000, v18
	v_sub_f32_e32 v16, v16, v25
	v_mul_f32_e32 v16, v23, v16
	v_fma_f32 v16, v5, v16, v13
	v_cvt_pk_bf16_f32 v16, v16, v16
	v_xad_u32 v17, v24, s20, v169
	ds_write_b16 v17, v16 offset:36096
	v_lshlrev_b32_e32 v16, 16, v19
	v_sub_f32_e32 v16, v16, v25
	v_mul_f32_e32 v16, v23, v16
	v_fma_f32 v16, v6, v16, v14
	v_cvt_pk_bf16_f32 v16, v16, v16
	v_xad_u32 v17, v24, s21, v169
	ds_write_b16 v17, v16 offset:36352
	v_and_b32_e32 v16, 0xffff0000, v19
	v_sub_f32_e32 v16, v16, v25
	v_mul_f32_e32 v16, v23, v16
	v_fma_f32 v16, v7, v16, v15
	v_xad_u32 v17, v24, s22, v169
	v_cvt_pk_bf16_f32 v16, v16, v16
	ds_write_b16 v17, v16 offset:36608
	v_add_co_u32_e32 v16, vcc, 0xffff0000, v20
	v_add_u32_e32 v23, s4, v170
	s_nop 0
	v_addc_co_u32_e32 v17, vcc, -1, v21, vcc
	v_add_u32_e32 v24, 0x19000, v23
	ds_read_b32 v24, v24
	v_add_u32_e32 v25, 0x19200, v23
	ds_read_b32 v25, v25
	v_lshrrev_b32_e32 v26, 3, v22
	v_xor_b32_e32 v26, v26, v168
	v_lshlrev_b32_e32 v26, 4, v26
	v_add_u32_e32 v28, v169, v26
	s_addk_i32 s4, 0x80
	s_mov_b64 s[8:9], 0x20000
	s_waitcnt vmcnt(1)
	v_mov_b32_e32 v16, v240
	v_mov_b32_e32 v17, v241
	v_mov_b32_e32 v18, v242
	v_mov_b32_e32 v19, v243
	v_lshlrev_b32_e32 v27, 16, v16
	s_waitcnt lgkmcnt(1)
	v_sub_f32_e32 v27, v27, v24
	v_and_b32_e32 v16, 0xffff0000, v16
	s_waitcnt lgkmcnt(0)
	v_mul_f32_e32 v27, v25, v27
	v_sub_f32_e32 v16, v16, v24
	v_fma_f32 v27, v0, v27, v8
	v_mul_f32_e32 v16, v25, v16
	v_cvt_pk_bf16_f32 v27, v27, v27
	v_fma_f32 v16, v1, v16, v9
	ds_write_b16 v28, v27 offset:34816
	v_cvt_pk_bf16_f32 v16, v16, v16
	v_xad_u32 v27, v26, 16, v169
	ds_write_b16 v27, v16 offset:35072
	v_lshlrev_b32_e32 v16, 16, v17
	v_sub_f32_e32 v16, v16, v24
	v_mul_f32_e32 v16, v25, v16
	v_fma_f32 v16, v2, v16, v10
	v_cvt_pk_bf16_f32 v16, v16, v16
	v_xad_u32 v27, v26, 32, v169
	ds_write_b16 v27, v16 offset:35328
	v_and_b32_e32 v16, 0xffff0000, v17
	v_sub_f32_e32 v16, v16, v24
	v_mul_f32_e32 v16, v25, v16
	v_fma_f32 v16, v3, v16, v11
	v_cvt_pk_bf16_f32 v16, v16, v16
	v_xad_u32 v17, v26, 48, v169
	ds_write_b16 v17, v16 offset:35584
	v_lshlrev_b32_e32 v16, 16, v18
	v_sub_f32_e32 v16, v16, v24
	v_mul_f32_e32 v16, v25, v16
	v_fma_f32 v16, v4, v16, v12
	v_cvt_pk_bf16_f32 v16, v16, v16
	v_xad_u32 v17, v26, 64, v169
	ds_write_b16 v17, v16 offset:35840
	v_and_b32_e32 v16, 0xffff0000, v18
	v_sub_f32_e32 v16, v16, v24
	v_mul_f32_e32 v16, v25, v16
	v_fma_f32 v16, v5, v16, v13
	v_cvt_pk_bf16_f32 v16, v16, v16
	v_xad_u32 v17, v26, s20, v169
	ds_write_b16 v17, v16 offset:36096
	v_lshlrev_b32_e32 v16, 16, v19
	v_sub_f32_e32 v16, v16, v24
	v_mul_f32_e32 v16, v25, v16
	v_fma_f32 v16, v6, v16, v14
	v_cvt_pk_bf16_f32 v16, v16, v16
	v_xad_u32 v17, v26, s21, v169
	ds_write_b16 v17, v16 offset:36352
	v_and_b32_e32 v16, 0xffff0000, v19
	v_sub_f32_e32 v16, v16, v24
	v_mul_f32_e32 v16, v25, v16
	v_fma_f32 v16, v7, v16, v15
	v_cvt_pk_bf16_f32 v16, v16, v16
	v_xad_u32 v17, v26, s22, v169
	ds_write_b16 v17, v16 offset:36608
	v_add_u32_e32 v25, 0x19040, v23
	ds_read_b32 v25, v25
	v_add_u32_e32 v23, 0x19240, v23
	ds_read_b32 v23, v23
	v_add_u32_e32 v24, 16, v22
	v_lshrrev_b32_e32 v24, 3, v24
	v_xor_b32_e32 v24, v24, v168
	v_lshlrev_b32_e32 v24, 4, v24
	v_add_u32_e32 v27, v169, v24
	v_add_u32_e32 v22, 32, v22
	v_lshl_add_u64 v[20:21], v[20:21], 0, s[8:9]
	s_waitcnt vmcnt(0)
	v_mov_b32_e32 v16, v244
	v_mov_b32_e32 v17, v245
	v_mov_b32_e32 v18, v246
	v_mov_b32_e32 v19, v247
	v_lshlrev_b32_e32 v26, 16, v16
	s_waitcnt lgkmcnt(1)
	v_sub_f32_e32 v26, v26, v25
	v_and_b32_e32 v16, 0xffff0000, v16
	s_waitcnt lgkmcnt(0)
	v_mul_f32_e32 v26, v23, v26
	v_sub_f32_e32 v16, v16, v25
	v_fma_f32 v26, v0, v26, v8
	v_mul_f32_e32 v16, v23, v16
	v_cvt_pk_bf16_f32 v26, v26, v26
	v_fma_f32 v16, v1, v16, v9
	ds_write_b16 v27, v26 offset:34816
	v_cvt_pk_bf16_f32 v16, v16, v16
	v_xad_u32 v26, v24, 16, v169
	ds_write_b16 v26, v16 offset:35072
	v_lshlrev_b32_e32 v16, 16, v17
	v_sub_f32_e32 v16, v16, v25
	v_mul_f32_e32 v16, v23, v16
	v_fma_f32 v16, v2, v16, v10
	v_cvt_pk_bf16_f32 v16, v16, v16
	v_xad_u32 v26, v24, 32, v169
	ds_write_b16 v26, v16 offset:35328
	v_and_b32_e32 v16, 0xffff0000, v17
	v_sub_f32_e32 v16, v16, v25
	v_mul_f32_e32 v16, v23, v16
	v_fma_f32 v16, v3, v16, v11
	v_cvt_pk_bf16_f32 v16, v16, v16
	v_xad_u32 v17, v24, 48, v169
	ds_write_b16 v17, v16 offset:35584
	v_lshlrev_b32_e32 v16, 16, v18
	v_sub_f32_e32 v16, v16, v25
	v_mul_f32_e32 v16, v23, v16
	v_fma_f32 v16, v4, v16, v12
	v_cvt_pk_bf16_f32 v16, v16, v16
	v_xad_u32 v17, v24, 64, v169
	ds_write_b16 v17, v16 offset:35840
	v_and_b32_e32 v16, 0xffff0000, v18
	v_sub_f32_e32 v16, v16, v25
	v_mul_f32_e32 v16, v23, v16
	v_fma_f32 v16, v5, v16, v13
	v_cvt_pk_bf16_f32 v16, v16, v16
	v_xad_u32 v17, v24, s20, v169
	ds_write_b16 v17, v16 offset:36096
	v_lshlrev_b32_e32 v16, 16, v19
	v_sub_f32_e32 v16, v16, v25
	v_mul_f32_e32 v16, v23, v16
	v_fma_f32 v16, v6, v16, v14
	v_cvt_pk_bf16_f32 v16, v16, v16
	v_xad_u32 v17, v24, s21, v169
	ds_write_b16 v17, v16 offset:36352
	v_and_b32_e32 v16, 0xffff0000, v19
	v_sub_f32_e32 v16, v16, v25
	v_mul_f32_e32 v16, v23, v16
	v_fma_f32 v16, v7, v16, v15
	v_xad_u32 v17, v24, s22, v169
	v_cvt_pk_bf16_f32 v16, v16, v16
	ds_write_b16 v17, v16 offset:36608
	s_waitcnt lgkmcnt(0)
	s_barrier
	ds_read_b128 v[0:3], v178 offset:34816
	ds_read_b128 v[4:7], v179 offset:34816
	ds_read_b128 v[8:11], v180
	ds_read_b128 v[12:15], v180 offset:4352
	ds_read_b128 v[16:19], v180 offset:8704
	ds_read_b128 v[20:23], v180 offset:13056
	ds_read_b128 v[24:27], v180 offset:17408
	ds_read_b128 v[28:31], v180 offset:21760
	ds_read_b128 v[32:35], v180 offset:26112
	ds_read_b128 v[36:39], v180 offset:30464
	s_waitcnt lgkmcnt(7)
	v_mfma_f32_16x16x32_bf16 v[40:43], v[0:3], v[8:11], 0
	s_add_i32 s12, s12, s96
	s_mov_b64 s[74:75], 0
	s_cmpk_gt_i32 s12, 0x7ff
	s_waitcnt lgkmcnt(6)
	v_mfma_f32_16x16x32_bf16 v[44:47], v[0:3], v[12:15], 0
	s_waitcnt lgkmcnt(5)
	v_mfma_f32_16x16x32_bf16 v[48:51], v[0:3], v[16:19], 0
	s_waitcnt lgkmcnt(4)
	v_mfma_f32_16x16x32_bf16 v[52:55], v[0:3], v[20:23], 0
	s_waitcnt lgkmcnt(3)
	v_mfma_f32_16x16x32_bf16 v[56:59], v[0:3], v[24:27], 0
	s_waitcnt lgkmcnt(2)
	v_mfma_f32_16x16x32_bf16 v[60:63], v[0:3], v[28:31], 0
	s_waitcnt lgkmcnt(1)
	v_mfma_f32_16x16x32_bf16 v[64:67], v[0:3], v[32:35], 0
	s_waitcnt lgkmcnt(0)
	v_mfma_f32_16x16x32_bf16 v[0:3], v[0:3], v[36:39], 0
	v_mfma_f32_16x16x32_bf16 v[8:11], v[4:7], v[8:11], 0
	v_mfma_f32_16x16x32_bf16 v[12:15], v[4:7], v[12:15], 0
	v_mfma_f32_16x16x32_bf16 v[16:19], v[4:7], v[16:19], 0
	v_mfma_f32_16x16x32_bf16 v[20:23], v[4:7], v[20:23], 0
	v_mfma_f32_16x16x32_bf16 v[24:27], v[4:7], v[24:27], 0
	v_mfma_f32_16x16x32_bf16 v[28:31], v[4:7], v[28:31], 0
	v_mfma_f32_16x16x32_bf16 v[32:35], v[4:7], v[32:35], 0
	v_mfma_f32_16x16x32_bf16 v[4:7], v[4:7], v[36:39], 0
	ds_read_b128 v[36:39], v181 offset:34816
	ds_read_b128 v[68:71], v182 offset:34816
	ds_read_b128 v[72:75], v180 offset:64
	ds_read_b128 v[76:79], v180 offset:4416
	ds_read_b128 v[80:83], v180 offset:8768
	ds_read_b128 v[132:135], v180 offset:13120
	ds_read_b128 v[136:139], v180 offset:17472
	ds_read_b128 v[142:145], v180 offset:21824
	ds_read_b128 v[146:149], v180 offset:26176
	ds_read_b128 v[150:153], v180 offset:30528
	s_waitcnt lgkmcnt(7)
	v_mfma_f32_16x16x32_bf16 v[40:43], v[36:39], v[72:75], v[40:43]
	s_waitcnt lgkmcnt(6)
	v_mfma_f32_16x16x32_bf16 v[44:47], v[36:39], v[76:79], v[44:47]
	s_waitcnt lgkmcnt(5)
	v_mfma_f32_16x16x32_bf16 v[48:51], v[36:39], v[80:83], v[48:51]
	s_waitcnt lgkmcnt(4)
	v_mfma_f32_16x16x32_bf16 v[52:55], v[36:39], v[132:135], v[52:55]
	s_waitcnt lgkmcnt(3)
	v_mfma_f32_16x16x32_bf16 v[56:59], v[36:39], v[136:139], v[56:59]
	s_waitcnt lgkmcnt(2)
	v_mfma_f32_16x16x32_bf16 v[60:63], v[36:39], v[142:145], v[60:63]
	s_waitcnt lgkmcnt(1)
	v_mfma_f32_16x16x32_bf16 v[64:67], v[36:39], v[146:149], v[64:67]
	s_waitcnt lgkmcnt(0)
	v_mfma_f32_16x16x32_bf16 v[0:3], v[36:39], v[150:153], v[0:3]
	v_mfma_f32_16x16x32_bf16 v[8:11], v[68:71], v[72:75], v[8:11]
	v_mfma_f32_16x16x32_bf16 v[12:15], v[68:71], v[76:79], v[12:15]
	v_mfma_f32_16x16x32_bf16 v[16:19], v[68:71], v[80:83], v[16:19]
	v_mfma_f32_16x16x32_bf16 v[20:23], v[68:71], v[132:135], v[20:23]
	v_mfma_f32_16x16x32_bf16 v[24:27], v[68:71], v[136:139], v[24:27]
	v_mfma_f32_16x16x32_bf16 v[28:31], v[68:71], v[142:145], v[28:31]
	v_mfma_f32_16x16x32_bf16 v[32:35], v[68:71], v[146:149], v[32:35]
	v_mfma_f32_16x16x32_bf16 v[4:7], v[68:71], v[150:153], v[4:7]
	ds_read_b128 v[36:39], v183 offset:34816
	ds_read_b128 v[68:71], v184 offset:34816
	ds_read_b128 v[72:75], v180 offset:128
	ds_read_b128 v[76:79], v180 offset:4480
	ds_read_b128 v[80:83], v180 offset:8832
	ds_read_b128 v[132:135], v180 offset:13184
	ds_read_b128 v[136:139], v180 offset:17536
	ds_read_b128 v[142:145], v180 offset:21888
	ds_read_b128 v[146:149], v180 offset:26240
	ds_read_b128 v[150:153], v180 offset:30592
	s_waitcnt lgkmcnt(7)
	v_mfma_f32_16x16x32_bf16 v[40:43], v[36:39], v[72:75], v[40:43]
	s_waitcnt lgkmcnt(6)
	v_mfma_f32_16x16x32_bf16 v[44:47], v[36:39], v[76:79], v[44:47]
	s_waitcnt lgkmcnt(5)
	v_mfma_f32_16x16x32_bf16 v[48:51], v[36:39], v[80:83], v[48:51]
	s_waitcnt lgkmcnt(4)
	v_mfma_f32_16x16x32_bf16 v[52:55], v[36:39], v[132:135], v[52:55]
	s_waitcnt lgkmcnt(3)
	v_mfma_f32_16x16x32_bf16 v[56:59], v[36:39], v[136:139], v[56:59]
	s_waitcnt lgkmcnt(2)
	v_mfma_f32_16x16x32_bf16 v[154:157], v[36:39], v[142:145], v[60:63]
	s_waitcnt lgkmcnt(1)
	v_mfma_f32_16x16x32_bf16 v[64:67], v[36:39], v[146:149], v[64:67]
	s_waitcnt lgkmcnt(0)
	v_mfma_f32_16x16x32_bf16 v[0:3], v[36:39], v[150:153], v[0:3]
	v_mfma_f32_16x16x32_bf16 v[8:11], v[68:71], v[72:75], v[8:11]
	v_mfma_f32_16x16x32_bf16 v[16:19], v[68:71], v[80:83], v[16:19]
	v_mfma_f32_16x16x32_bf16 v[36:39], v[68:71], v[132:135], v[20:23]
	v_mfma_f32_16x16x32_bf16 v[24:27], v[68:71], v[136:139], v[24:27]
	v_mfma_f32_16x16x32_bf16 v[28:31], v[68:71], v[142:145], v[28:31]
	v_mfma_f32_16x16x32_bf16 v[32:35], v[68:71], v[146:149], v[32:35]
	v_mfma_f32_16x16x32_bf16 v[4:7], v[68:71], v[150:153], v[4:7]
	ds_read_b128 v[20:23], v185 offset:34816
	ds_read_b128 v[132:135], v186 offset:34816
	ds_read_b128 v[72:75], v180 offset:192
	ds_read_b128 v[80:83], v180 offset:4544
	ds_read_b128 v[136:139], v180 offset:8896
	ds_read_b128 v[142:145], v180 offset:13248
	ds_read_b128 v[146:149], v180 offset:17600
	ds_read_b128 v[150:153], v180 offset:21952
	ds_read_b128 v[158:161], v180 offset:26304
	ds_read_b128 v[162:165], v180 offset:30656
	v_mfma_f32_16x16x32_bf16 v[12:15], v[68:71], v[76:79], v[12:15]
	s_waitcnt lgkmcnt(7)
	v_mfma_f32_16x16x32_bf16 v[188:191], v[20:23], v[72:75], v[40:43]
	s_waitcnt lgkmcnt(6)
	v_mfma_f32_16x16x32_bf16 v[192:195], v[20:23], v[80:83], v[44:47]
	s_waitcnt lgkmcnt(5)
	v_mfma_f32_16x16x32_bf16 v[76:79], v[20:23], v[136:139], v[48:51]
	s_waitcnt lgkmcnt(4)
	v_mfma_f32_16x16x32_bf16 v[68:71], v[20:23], v[142:145], v[52:55]
	s_waitcnt lgkmcnt(3)
	v_mfma_f32_16x16x32_bf16 v[60:63], v[20:23], v[146:149], v[56:59]
	s_waitcnt lgkmcnt(2)
	v_mfma_f32_16x16x32_bf16 v[52:55], v[20:23], v[150:153], v[154:157]
	s_waitcnt lgkmcnt(1)
	v_mfma_f32_16x16x32_bf16 v[44:47], v[20:23], v[158:161], v[64:67]
	s_waitcnt lgkmcnt(0)
	v_mfma_f32_16x16x32_bf16 v[20:23], v[20:23], v[162:165], v[0:3]
	v_mfma_f32_16x16x32_bf16 v[56:59], v[132:135], v[146:149], v[24:27]
	v_mfma_f32_16x16x32_bf16 v[24:27], v[132:135], v[162:165], v[4:7]
	v_lshl_add_u64 v[164:165], s[6:7], 0, v[86:87]
	v_lshlrev_b64 v[0:1], 12, v[164:165]
	v_lshl_add_u64 v[0:1], v[88:89], 0, v[0:1]
	v_lshl_add_u64 v[162:163], s[6:7], 0, v[112:113]
	global_load_dwordx4 v[40:43], v[0:1], off
	v_lshlrev_b64 v[0:1], 12, v[162:163]
	v_mfma_f32_16x16x32_bf16 v[64:67], v[132:135], v[142:145], v[36:39]
	v_lshl_add_u64 v[0:1], v[88:89], 0, v[0:1]
	v_mfma_f32_16x16x32_bf16 v[36:39], v[132:135], v[158:161], v[32:35]
	v_lshl_add_u64 v[160:161], s[6:7], 0, v[114:115]
	v_lshl_add_u64 v[158:159], s[6:7], 0, v[116:117]
	s_nop 0
	global_load_dwordx4 v[32:35], v[0:1], off
	v_lshlrev_b64 v[0:1], 12, v[160:161]
	v_lshl_add_u64 v[0:1], v[88:89], 0, v[0:1]
	v_mfma_f32_16x16x32_bf16 v[48:51], v[132:135], v[150:153], v[28:31]
	s_nop 2
	global_load_dwordx4 v[28:31], v[0:1], off
	v_lshlrev_b64 v[0:1], 12, v[158:159]
	v_mfma_f32_16x16x32_bf16 v[154:157], v[132:135], v[72:75], v[8:11]
	v_lshl_add_u64 v[0:1], v[88:89], 0, v[0:1]
	v_mfma_f32_16x16x32_bf16 v[72:75], v[132:135], v[136:139], v[16:19]
	v_lshl_add_u64 v[138:139], s[6:7], 0, v[118:119]
	v_lshl_add_u64 v[136:137], s[6:7], 0, v[120:121]
	s_nop 0
	global_load_dwordx4 v[16:19], v[0:1], off
	v_lshlrev_b64 v[0:1], 12, v[138:139]
	v_lshl_add_u64 v[0:1], v[88:89], 0, v[0:1]
	v_mfma_f32_16x16x32_bf16 v[80:83], v[132:135], v[80:83], v[12:15]
	v_lshl_add_u64 v[134:135], s[6:7], 0, v[122:123]
	v_lshl_add_u64 v[132:133], s[6:7], 0, v[124:125]
	s_nop 0
	global_load_dwordx4 v[12:15], v[0:1], off
	v_lshlrev_b64 v[0:1], 12, v[136:137]
	v_lshl_add_u64 v[0:1], v[88:89], 0, v[0:1]
	global_load_dwordx4 v[8:11], v[0:1], off
	v_lshlrev_b64 v[0:1], 12, v[134:135]
	v_lshl_add_u64 v[0:1], v[88:89], 0, v[0:1]
	global_load_dwordx4 v[4:7], v[0:1], off
	v_lshlrev_b64 v[0:1], 12, v[132:133]
	v_lshl_add_u64 v[0:1], v[88:89], 0, v[0:1]
	global_load_dwordx4 v[0:3], v[0:1], off
	s_barrier
	v_mov_b32_e32 v142, v197
	s_nop 0
	v_pk_add_f32 v[144:145], v[190:191], v[142:143] op_sel_hi:[1,0]
	v_pk_add_f32 v[146:147], v[188:189], v[142:143] op_sel_hi:[1,0]
	s_nop 0
	v_cvt_pk_bf16_f32 v146, v146, v147
	v_cvt_pk_bf16_f32 v147, v144, v145
	v_pk_add_f32 v[144:145], v[156:157], v[142:143] op_sel_hi:[1,0]
	v_pk_add_f32 v[142:143], v[154:155], v[142:143] op_sel_hi:[1,0]
	ds_write_b64 v187, v[146:147] offset:34816
	v_cvt_pk_bf16_f32 v142, v142, v143
	v_cvt_pk_bf16_f32 v143, v144, v145
	ds_write_b64 v187, v[142:143] offset:34848
	v_mov_b32_e32 v142, v200
	s_nop 0
	v_pk_add_f32 v[146:147], v[192:193], v[142:143] op_sel_hi:[1,0]
	v_pk_add_f32 v[80:81], v[80:81], v[142:143] op_sel_hi:[1,0]
	v_pk_add_f32 v[144:145], v[194:195], v[142:143] op_sel_hi:[1,0]
	v_cvt_pk_bf16_f32 v146, v146, v147
	v_pk_add_f32 v[82:83], v[82:83], v[142:143] op_sel_hi:[1,0]
	v_cvt_pk_bf16_f32 v147, v144, v145
	ds_write_b64 v187, v[146:147] offset:43264
	v_cvt_pk_bf16_f32 v80, v80, v81
	v_cvt_pk_bf16_f32 v81, v82, v83
	ds_write_b64 v187, v[80:81] offset:43296
	v_mov_b32_e32 v80, v201
	s_nop 0
	v_pk_add_f32 v[76:77], v[76:77], v[80:81] op_sel_hi:[1,0]
	v_pk_add_f32 v[72:73], v[72:73], v[80:81] op_sel_hi:[1,0]
	v_pk_add_f32 v[78:79], v[78:79], v[80:81] op_sel_hi:[1,0]
	v_cvt_pk_bf16_f32 v76, v76, v77
	v_pk_add_f32 v[74:75], v[74:75], v[80:81] op_sel_hi:[1,0]
	v_cvt_pk_bf16_f32 v77, v78, v79
	ds_write_b64 v187, v[76:77] offset:51712
	v_cvt_pk_bf16_f32 v72, v72, v73
	v_cvt_pk_bf16_f32 v73, v74, v75
	ds_write_b64 v187, v[72:73] offset:51744
	v_mov_b32_e32 v72, v202
	s_nop 0
	v_pk_add_f32 v[68:69], v[68:69], v[72:73] op_sel_hi:[1,0]
	v_pk_add_f32 v[64:65], v[64:65], v[72:73] op_sel_hi:[1,0]
	v_pk_add_f32 v[70:71], v[70:71], v[72:73] op_sel_hi:[1,0]
	v_cvt_pk_bf16_f32 v68, v68, v69
	v_pk_add_f32 v[66:67], v[66:67], v[72:73] op_sel_hi:[1,0]
	v_cvt_pk_bf16_f32 v69, v70, v71
	ds_write_b64 v187, v[68:69] offset:60160
	v_cvt_pk_bf16_f32 v64, v64, v65
	v_cvt_pk_bf16_f32 v65, v66, v67
	ds_write_b64 v187, v[64:65] offset:60192
	v_mov_b32_e32 v64, v203
	s_nop 0
	v_pk_add_f32 v[60:61], v[60:61], v[64:65] op_sel_hi:[1,0]
	v_pk_add_f32 v[56:57], v[56:57], v[64:65] op_sel_hi:[1,0]
	v_pk_add_f32 v[62:63], v[62:63], v[64:65] op_sel_hi:[1,0]
	v_cvt_pk_bf16_f32 v60, v60, v61
	v_pk_add_f32 v[58:59], v[58:59], v[64:65] op_sel_hi:[1,0]
	v_cvt_pk_bf16_f32 v61, v62, v63
	ds_write_b64 v206, v[60:61] offset:34816
	v_cvt_pk_bf16_f32 v56, v56, v57
	v_cvt_pk_bf16_f32 v57, v58, v59
	ds_write_b64 v206, v[56:57] offset:34848
	v_mov_b32_e32 v56, v204
	s_nop 0
	v_pk_add_f32 v[52:53], v[52:53], v[56:57] op_sel_hi:[1,0]
	v_pk_add_f32 v[48:49], v[48:49], v[56:57] op_sel_hi:[1,0]
	v_pk_add_f32 v[54:55], v[54:55], v[56:57] op_sel_hi:[1,0]
	v_cvt_pk_bf16_f32 v52, v52, v53
	v_pk_add_f32 v[50:51], v[50:51], v[56:57] op_sel_hi:[1,0]
	v_cvt_pk_bf16_f32 v53, v54, v55
	ds_write_b64 v206, v[52:53] offset:43264
	v_cvt_pk_bf16_f32 v48, v48, v49
	v_cvt_pk_bf16_f32 v49, v50, v51
	ds_write_b64 v206, v[48:49] offset:43296
	v_mov_b32_e32 v48, v215
	s_nop 0
	v_pk_add_f32 v[44:45], v[44:45], v[48:49] op_sel_hi:[1,0]
	v_pk_add_f32 v[36:37], v[36:37], v[48:49] op_sel_hi:[1,0]
	v_pk_add_f32 v[46:47], v[46:47], v[48:49] op_sel_hi:[1,0]
	v_cvt_pk_bf16_f32 v44, v44, v45
	v_pk_add_f32 v[38:39], v[38:39], v[48:49] op_sel_hi:[1,0]
	v_cvt_pk_bf16_f32 v45, v46, v47
	ds_write_b64 v206, v[44:45] offset:51712
	v_cvt_pk_bf16_f32 v36, v36, v37
	v_cvt_pk_bf16_f32 v37, v38, v39
	ds_write_b64 v206, v[36:37] offset:51744
	v_mov_b32_e32 v36, v249
	s_waitcnt vmcnt(0)
	v_pk_add_f32 v[22:23], v[22:23], v[36:37] op_sel_hi:[1,0]
	v_pk_add_f32 v[20:21], v[20:21], v[36:37] op_sel_hi:[1,0]
	s_nop 0
	v_cvt_pk_bf16_f32 v20, v20, v21
	v_cvt_pk_bf16_f32 v21, v22, v23
	v_pk_add_f32 v[22:23], v[24:25], v[36:37] op_sel_hi:[1,0]
	ds_write_b64 v206, v[20:21] offset:60160
	v_pk_add_f32 v[20:21], v[26:27], v[36:37] op_sel_hi:[1,0]
	v_cvt_pk_bf16_f32 v22, v22, v23
	v_lshlrev_b32_e32 v24, 16, v40
	v_cvt_pk_bf16_f32 v23, v20, v21
	ds_write_b64 v206, v[22:23] offset:60192
	s_waitcnt lgkmcnt(0)
	s_barrier
	ds_read_b128 v[20:23], v207 offset:34816
	s_waitcnt lgkmcnt(0)
	v_lshlrev_b32_e32 v25, 16, v20
	v_mul_f32_e32 v24, v25, v24
	v_and_b32_e32 v20, 0xffff0000, v20
	v_and_b32_e32 v25, 0xffff0000, v40
	v_mul_f32_e32 v20, v20, v25
	v_cvt_pk_bf16_f32 v20, v24, v20
	v_lshlrev_b32_e32 v24, 16, v41
	v_lshlrev_b32_e32 v25, 16, v21
	v_mul_f32_e32 v24, v25, v24
	v_and_b32_e32 v21, 0xffff0000, v21
	v_and_b32_e32 v25, 0xffff0000, v41
	v_mul_f32_e32 v21, v21, v25
	v_cvt_pk_bf16_f32 v21, v24, v21
	v_lshlrev_b32_e32 v24, 16, v42
	v_lshlrev_b32_e32 v25, 16, v22
	v_mul_f32_e32 v24, v25, v24
	v_and_b32_e32 v22, 0xffff0000, v22
	v_and_b32_e32 v25, 0xffff0000, v42
	v_mul_f32_e32 v22, v22, v25
	v_cvt_pk_bf16_f32 v22, v24, v22
	v_lshlrev_b32_e32 v24, 16, v43
	v_lshlrev_b32_e32 v25, 16, v23
	v_mul_f32_e32 v24, v25, v24
	v_and_b32_e32 v23, 0xffff0000, v23
	v_and_b32_e32 v25, 0xffff0000, v43
	v_mul_f32_e32 v23, v23, v25
	v_cvt_pk_bf16_f32 v23, v24, v23
	v_lshlrev_b64 v[24:25], 11, v[164:165]
	v_lshl_add_u64 v[24:25], v[90:91], 0, v[24:25]
	global_store_dwordx4 v[24:25], v[20:23], off nt
	ds_read_b128 v[20:23], v208 offset:34816
	v_lshlrev_b32_e32 v24, 16, v32
	s_waitcnt lgkmcnt(0)
	v_lshlrev_b32_e32 v25, 16, v20
	v_mul_f32_e32 v24, v25, v24
	v_and_b32_e32 v20, 0xffff0000, v20
	v_and_b32_e32 v25, 0xffff0000, v32
	v_mul_f32_e32 v20, v20, v25
	v_cvt_pk_bf16_f32 v20, v24, v20
	v_lshlrev_b32_e32 v24, 16, v33
	v_lshlrev_b32_e32 v25, 16, v21
	v_mul_f32_e32 v24, v25, v24
	v_and_b32_e32 v21, 0xffff0000, v21
	v_and_b32_e32 v25, 0xffff0000, v33
	v_mul_f32_e32 v21, v21, v25
	v_cvt_pk_bf16_f32 v21, v24, v21
	v_lshlrev_b32_e32 v24, 16, v34
	v_lshlrev_b32_e32 v25, 16, v22
	v_mul_f32_e32 v24, v25, v24
	v_and_b32_e32 v22, 0xffff0000, v22
	v_and_b32_e32 v25, 0xffff0000, v34
	v_mul_f32_e32 v22, v22, v25
	v_cvt_pk_bf16_f32 v22, v24, v22
	v_lshlrev_b32_e32 v24, 16, v35
	v_lshlrev_b32_e32 v25, 16, v23
	v_mul_f32_e32 v24, v25, v24
	v_and_b32_e32 v23, 0xffff0000, v23
	v_and_b32_e32 v25, 0xffff0000, v35
	v_mul_f32_e32 v23, v23, v25
	v_cvt_pk_bf16_f32 v23, v24, v23
	v_lshlrev_b64 v[24:25], 11, v[162:163]
	v_lshl_add_u64 v[24:25], v[90:91], 0, v[24:25]
	global_store_dwordx4 v[24:25], v[20:23], off nt
	ds_read_b128 v[20:23], v209 offset:34816
	v_lshlrev_b32_e32 v24, 16, v28
	s_waitcnt lgkmcnt(0)
	v_lshlrev_b32_e32 v25, 16, v20
	v_mul_f32_e32 v24, v25, v24
	v_and_b32_e32 v20, 0xffff0000, v20
	v_and_b32_e32 v25, 0xffff0000, v28
	v_mul_f32_e32 v20, v20, v25
	v_cvt_pk_bf16_f32 v20, v24, v20
	v_lshlrev_b32_e32 v24, 16, v29
	v_lshlrev_b32_e32 v25, 16, v21
	v_mul_f32_e32 v24, v25, v24
	v_and_b32_e32 v21, 0xffff0000, v21
	v_and_b32_e32 v25, 0xffff0000, v29
	v_mul_f32_e32 v21, v21, v25
	v_cvt_pk_bf16_f32 v21, v24, v21
	v_lshlrev_b32_e32 v24, 16, v30
	v_lshlrev_b32_e32 v25, 16, v22
	v_mul_f32_e32 v24, v25, v24
	v_and_b32_e32 v22, 0xffff0000, v22
	v_and_b32_e32 v25, 0xffff0000, v30
	v_mul_f32_e32 v22, v22, v25
	v_cvt_pk_bf16_f32 v22, v24, v22
	v_lshlrev_b32_e32 v24, 16, v31
	v_lshlrev_b32_e32 v25, 16, v23
	v_mul_f32_e32 v24, v25, v24
	v_and_b32_e32 v23, 0xffff0000, v23
	v_and_b32_e32 v25, 0xffff0000, v31
	v_mul_f32_e32 v23, v23, v25
	v_cvt_pk_bf16_f32 v23, v24, v23
	v_lshlrev_b64 v[24:25], 11, v[160:161]
	v_lshl_add_u64 v[24:25], v[90:91], 0, v[24:25]
	global_store_dwordx4 v[24:25], v[20:23], off nt
	ds_read_b128 v[20:23], v210 offset:34816
	v_lshlrev_b32_e32 v24, 16, v16
	v_and_b32_e32 v16, 0xffff0000, v16
	s_waitcnt lgkmcnt(0)
	v_lshlrev_b32_e32 v25, 16, v20
	v_and_b32_e32 v20, 0xffff0000, v20
	v_mul_f32_e32 v24, v25, v24
	v_mul_f32_e32 v16, v20, v16
	v_cvt_pk_bf16_f32 v16, v24, v16
	v_lshlrev_b32_e32 v20, 16, v17
	v_lshlrev_b32_e32 v24, 16, v21
	v_and_b32_e32 v21, 0xffff0000, v21
	v_and_b32_e32 v17, 0xffff0000, v17
	v_mul_f32_e32 v20, v24, v20
	v_mul_f32_e32 v17, v21, v17
	v_cvt_pk_bf16_f32 v17, v20, v17
	v_lshlrev_b32_e32 v20, 16, v18
	v_lshlrev_b32_e32 v21, 16, v22
	v_mul_f32_e32 v20, v21, v20
	v_and_b32_e32 v21, 0xffff0000, v22
	v_and_b32_e32 v18, 0xffff0000, v18
	v_mul_f32_e32 v18, v21, v18
	v_cvt_pk_bf16_f32 v18, v20, v18
	v_lshlrev_b32_e32 v20, 16, v19
	v_lshlrev_b32_e32 v21, 16, v23
	v_mul_f32_e32 v20, v21, v20
	v_and_b32_e32 v21, 0xffff0000, v23
	v_and_b32_e32 v19, 0xffff0000, v19
	v_mul_f32_e32 v19, v21, v19
	v_cvt_pk_bf16_f32 v19, v20, v19
	v_lshlrev_b64 v[20:21], 11, v[158:159]
	v_lshl_add_u64 v[20:21], v[90:91], 0, v[20:21]
	global_store_dwordx4 v[20:21], v[16:19], off nt
	ds_read_b128 v[16:19], v211 offset:34816
	v_lshlrev_b32_e32 v20, 16, v12
	v_and_b32_e32 v12, 0xffff0000, v12
	s_waitcnt lgkmcnt(0)
	v_lshlrev_b32_e32 v21, 16, v16
	v_and_b32_e32 v16, 0xffff0000, v16
	v_mul_f32_e32 v20, v21, v20
	v_mul_f32_e32 v12, v16, v12
	v_cvt_pk_bf16_f32 v12, v20, v12
	v_lshlrev_b32_e32 v16, 16, v13
	v_lshlrev_b32_e32 v20, 16, v17
	v_and_b32_e32 v17, 0xffff0000, v17
	v_and_b32_e32 v13, 0xffff0000, v13
	v_mul_f32_e32 v16, v20, v16
	v_mul_f32_e32 v13, v17, v13
	v_cvt_pk_bf16_f32 v13, v16, v13
	v_lshlrev_b32_e32 v16, 16, v14
	v_lshlrev_b32_e32 v17, 16, v18
	v_mul_f32_e32 v16, v17, v16
	v_and_b32_e32 v17, 0xffff0000, v18
	v_and_b32_e32 v14, 0xffff0000, v14
	v_mul_f32_e32 v14, v17, v14
	v_cvt_pk_bf16_f32 v14, v16, v14
	v_lshlrev_b32_e32 v16, 16, v15
	v_lshlrev_b32_e32 v17, 16, v19
	v_mul_f32_e32 v16, v17, v16
	v_and_b32_e32 v17, 0xffff0000, v19
	v_and_b32_e32 v15, 0xffff0000, v15
	v_mul_f32_e32 v15, v17, v15
	v_cvt_pk_bf16_f32 v15, v16, v15
	v_lshlrev_b64 v[16:17], 11, v[138:139]
	v_lshl_add_u64 v[16:17], v[90:91], 0, v[16:17]
	global_store_dwordx4 v[16:17], v[12:15], off nt
	ds_read_b128 v[12:15], v212 offset:34816
	v_lshlrev_b32_e32 v16, 16, v8
	v_and_b32_e32 v8, 0xffff0000, v8
	s_waitcnt lgkmcnt(0)
	v_lshlrev_b32_e32 v17, 16, v12
	v_and_b32_e32 v12, 0xffff0000, v12
	v_mul_f32_e32 v16, v17, v16
	v_mul_f32_e32 v8, v12, v8
	v_cvt_pk_bf16_f32 v8, v16, v8
	v_lshlrev_b32_e32 v12, 16, v9
	v_lshlrev_b32_e32 v16, 16, v13
	v_and_b32_e32 v13, 0xffff0000, v13
	v_and_b32_e32 v9, 0xffff0000, v9
	v_mul_f32_e32 v12, v16, v12
	v_mul_f32_e32 v9, v13, v9
	v_cvt_pk_bf16_f32 v9, v12, v9
	v_lshlrev_b32_e32 v12, 16, v10
	v_lshlrev_b32_e32 v13, 16, v14
	v_mul_f32_e32 v12, v13, v12
	v_and_b32_e32 v13, 0xffff0000, v14
	v_and_b32_e32 v10, 0xffff0000, v10
	v_mul_f32_e32 v10, v13, v10
	v_cvt_pk_bf16_f32 v10, v12, v10
	v_lshlrev_b32_e32 v12, 16, v11
	v_lshlrev_b32_e32 v13, 16, v15
	v_mul_f32_e32 v12, v13, v12
	v_and_b32_e32 v13, 0xffff0000, v15
	v_and_b32_e32 v11, 0xffff0000, v11
	v_mul_f32_e32 v11, v13, v11
	v_cvt_pk_bf16_f32 v11, v12, v11
	v_lshlrev_b64 v[12:13], 11, v[136:137]
	v_lshl_add_u64 v[12:13], v[90:91], 0, v[12:13]
	global_store_dwordx4 v[12:13], v[8:11], off nt
	ds_read_b128 v[8:11], v213 offset:34816
	v_lshlrev_b32_e32 v12, 16, v4
	v_and_b32_e32 v4, 0xffff0000, v4
	s_waitcnt lgkmcnt(0)
	v_lshlrev_b32_e32 v13, 16, v8
	v_and_b32_e32 v8, 0xffff0000, v8
	v_mul_f32_e32 v12, v13, v12
	v_mul_f32_e32 v4, v8, v4
	v_cvt_pk_bf16_f32 v4, v12, v4
	v_lshlrev_b32_e32 v8, 16, v5
	v_lshlrev_b32_e32 v12, 16, v9
	v_and_b32_e32 v9, 0xffff0000, v9
	v_and_b32_e32 v5, 0xffff0000, v5
	v_mul_f32_e32 v8, v12, v8
	v_mul_f32_e32 v5, v9, v5
	v_cvt_pk_bf16_f32 v5, v8, v5
	v_lshlrev_b32_e32 v8, 16, v6
	v_lshlrev_b32_e32 v9, 16, v10
	v_mul_f32_e32 v8, v9, v8
	v_and_b32_e32 v9, 0xffff0000, v10
	v_and_b32_e32 v6, 0xffff0000, v6
	v_mul_f32_e32 v6, v9, v6
	v_cvt_pk_bf16_f32 v6, v8, v6
	v_lshlrev_b32_e32 v8, 16, v7
	v_lshlrev_b32_e32 v9, 16, v11
	v_mul_f32_e32 v8, v9, v8
	v_and_b32_e32 v9, 0xffff0000, v11
	v_and_b32_e32 v7, 0xffff0000, v7
	v_mul_f32_e32 v7, v9, v7
	v_cvt_pk_bf16_f32 v7, v8, v7
	v_lshlrev_b64 v[8:9], 11, v[134:135]
	v_lshl_add_u64 v[8:9], v[90:91], 0, v[8:9]
	global_store_dwordx4 v[8:9], v[4:7], off nt
	ds_read_b128 v[4:7], v214 offset:34816
	v_lshlrev_b32_e32 v8, 16, v0
	v_and_b32_e32 v0, 0xffff0000, v0
	s_waitcnt lgkmcnt(0)
	v_lshlrev_b32_e32 v9, 16, v4
	v_and_b32_e32 v4, 0xffff0000, v4
	v_mul_f32_e32 v8, v9, v8
	v_mul_f32_e32 v0, v4, v0
	v_cvt_pk_bf16_f32 v0, v8, v0
	v_lshlrev_b32_e32 v4, 16, v1
	v_lshlrev_b32_e32 v8, 16, v5
	v_and_b32_e32 v5, 0xffff0000, v5
	v_and_b32_e32 v1, 0xffff0000, v1
	v_mul_f32_e32 v4, v8, v4
	v_mul_f32_e32 v1, v5, v1
	v_cvt_pk_bf16_f32 v1, v4, v1
	v_lshlrev_b32_e32 v4, 16, v2
	v_lshlrev_b32_e32 v5, 16, v6
	v_mul_f32_e32 v4, v5, v4
	v_and_b32_e32 v5, 0xffff0000, v6
	v_and_b32_e32 v2, 0xffff0000, v2
	v_mul_f32_e32 v2, v5, v2
	v_cvt_pk_bf16_f32 v2, v4, v2
	v_lshlrev_b32_e32 v4, 16, v3
	v_lshlrev_b32_e32 v5, 16, v7
	v_mul_f32_e32 v4, v5, v4
	v_and_b32_e32 v5, 0xffff0000, v7
	v_and_b32_e32 v3, 0xffff0000, v3
	v_mul_f32_e32 v3, v5, v3
	v_cvt_pk_bf16_f32 v3, v4, v3
	v_lshlrev_b64 v[4:5], 11, v[132:133]
	v_lshl_add_u64 v[4:5], v[90:91], 0, v[4:5]
	global_store_dwordx4 v[4:5], v[0:3], off nt
	s_cbranch_scc0 .LBB0_482
	s_mov_b32 s50, s24
	s_mov_b32 s52, s28

.LBB0_617:
	s_or_b64 exec, exec, s[10:11]
	s_andn2_b64 vcc, exec, s[8:9]
	s_mov_b32 s24, 0x3d800000
	s_waitcnt lgkmcnt(0)
	s_barrier
	s_cbranch_vccnz .LBB0_619
	s_ashr_i32 s7, s6, 31
	s_lshl_b64 s[4:5], s[6:7], 11
	v_lshl_add_u64 v[32:33], v[0:1], 0, s[4:5]
	v_add_co_u32_e32 v116, vcc, 0xffff9000, v32
	s_nop 1
	v_addc_co_u32_e32 v117, vcc, -1, v33, vcc
	v_add_co_u32_e32 v118, vcc, 0xffffb000, v32
	s_nop 1
	v_addc_co_u32_e32 v119, vcc, -1, v33, vcc
	v_add_co_u32_e32 v120, vcc, 0xffffd000, v32
	s_nop 1
	v_addc_co_u32_e32 v121, vcc, -1, v33, vcc
	v_add_co_u32_e32 v122, vcc, 0xfffff000, v32
	s_nop 1
	v_addc_co_u32_e32 v123, vcc, -1, v33, vcc
	global_load_dword v100, v[116:117], off offset:-2048
	global_load_dword v101, v[116:117], off
	global_load_dword v102, v[116:117], off offset:2048
	global_load_dword v103, v[118:119], off offset:-4096
	global_load_dword v104, v[118:119], off offset:-2048
	global_load_dword v105, v[118:119], off
	global_load_dword v106, v[118:119], off offset:2048
	global_load_dword v107, v[120:121], off offset:-4096
	global_load_dword v108, v[120:121], off offset:-2048
	global_load_dword v109, v[120:121], off
	global_load_dword v110, v[120:121], off offset:2048
	global_load_dword v111, v[122:123], off offset:-4096
	global_load_dword v112, v[122:123], off offset:-2048
	global_load_dword v113, v[122:123], off
	global_load_dword v114, v[122:123], off offset:2048
	v_add_co_u32_e32 v4, vcc, 0xffff9000, v32
	ds_read2_b32 v[8:9], v141 offset0:1 offset1:2
	ds_read2_b32 v[10:11], v141 offset0:5 offset1:6
	ds_read2_b32 v[26:27], v141 offset0:9 offset1:10
	ds_read2_b32 v[34:35], v141 offset0:13 offset1:14
	v_addc_co_u32_e32 v5, vcc, -1, v33, vcc
	s_waitcnt vmcnt(0)
	v_mov_b32_e32 v7, v100
	s_movk_i32 s4, 0xa000
	s_waitcnt vmcnt(0)
	v_mov_b32_e32 v5, v101
	s_movk_i32 s2, 0xb000
	ds_read2_b32 v[14:15], v141 offset0:7 offset1:8
	ds_read2_b32 v[28:29], v141 offset0:11 offset1:12
	s_waitcnt vmcnt(1)
	v_lshlrev_b32_e32 v6, 16, v7
	v_and_b32_e32 v7, 0xffff0000, v7
	s_waitcnt vmcnt(0)
	v_lshlrev_b32_e32 v4, 16, v5
	v_and_b32_e32 v5, 0xffff0000, v5
	s_waitcnt lgkmcnt(5)
	v_pk_mul_f32 v[16:17], v[8:9], v[4:5] op_sel:[1,0]
	v_add_co_u32_e32 v4, vcc, s4, v32
	v_pk_mul_f32 v[20:21], v[8:9], v[6:7] op_sel_hi:[0,1]
	s_nop 0
	v_addc_co_u32_e32 v5, vcc, -1, v33, vcc
	s_waitcnt vmcnt(0)
	v_mov_b32_e32 v5, v102
	ds_read2_b32 v[6:7], v141 offset0:3 offset1:4
	s_movk_i32 s4, 0xd000
	s_waitcnt vmcnt(0)
	v_lshlrev_b32_e32 v4, 16, v5
	v_and_b32_e32 v5, 0xffff0000, v5
	s_waitcnt lgkmcnt(0)
	v_pk_mul_f32 v[12:13], v[6:7], v[4:5] op_sel_hi:[0,1]
	v_add_co_u32_e32 v4, vcc, s2, v32
	s_movk_i32 s2, 0xc000
	s_nop 0
	v_addc_co_u32_e32 v5, vcc, -1, v33, vcc
	s_waitcnt vmcnt(0)
	v_mov_b32_e32 v9, v103
	s_waitcnt vmcnt(0)
	v_lshlrev_b32_e32 v8, 16, v9
	v_and_b32_e32 v9, 0xffff0000, v9
	v_pk_mul_f32 v[8:9], v[6:7], v[8:9] op_sel:[1,0]
	s_waitcnt vmcnt(0)
	v_mov_b32_e32 v7, v104
	s_waitcnt vmcnt(0)
	v_lshlrev_b32_e32 v6, 16, v7
	s_waitcnt vmcnt(0)
	v_mov_b32_e32 v5, v105
	v_and_b32_e32 v7, 0xffff0000, v7
	v_pk_mul_f32 v[6:7], v[10:11], v[6:7] op_sel_hi:[0,1]
	s_waitcnt vmcnt(0)
	v_lshlrev_b32_e32 v4, 16, v5
	v_and_b32_e32 v5, 0xffff0000, v5
	v_pk_mul_f32 v[4:5], v[10:11], v[4:5] op_sel:[1,0]
	v_add_co_u32_e32 v10, vcc, s2, v32
	s_nop 1
	v_addc_co_u32_e32 v11, vcc, -1, v33, vcc
	s_waitcnt vmcnt(0)
	v_mov_b32_e32 v11, v106
	s_waitcnt vmcnt(0)
	v_lshlrev_b32_e32 v10, 16, v11
	v_and_b32_e32 v11, 0xffff0000, v11
	v_pk_mul_f32 v[24:25], v[14:15], v[10:11] op_sel_hi:[0,1]
	v_add_co_u32_e32 v10, vcc, s4, v32
	s_movk_i32 s4, 0xe000
	s_nop 0
	v_addc_co_u32_e32 v11, vcc, -1, v33, vcc
	s_waitcnt vmcnt(0)
	v_mov_b32_e32 v19, v107
	s_waitcnt vmcnt(0)
	v_lshlrev_b32_e32 v18, 16, v19
	v_and_b32_e32 v19, 0xffff0000, v19
	v_pk_mul_f32 v[22:23], v[14:15], v[18:19] op_sel:[1,0]
	s_waitcnt vmcnt(0)
	v_mov_b32_e32 v15, v108
	s_waitcnt vmcnt(0)
	v_lshlrev_b32_e32 v14, 16, v15
	s_waitcnt vmcnt(0)
	v_mov_b32_e32 v11, v109
	v_and_b32_e32 v15, 0xffff0000, v15
	v_pk_mul_f32 v[18:19], v[26:27], v[14:15] op_sel_hi:[0,1]
	v_add_co_u32_e32 v14, vcc, s4, v32
	s_movk_i32 s4, 0xf000
	s_nop 0
	v_addc_co_u32_e32 v15, vcc, -1, v33, vcc
	s_waitcnt vmcnt(0)
	v_lshlrev_b32_e32 v10, 16, v11
	v_and_b32_e32 v11, 0xffff0000, v11
	v_pk_mul_f32 v[10:11], v[26:27], v[10:11] op_sel:[1,0]
	s_waitcnt vmcnt(0)
	v_mov_b32_e32 v27, v110
	s_waitcnt vmcnt(0)
	v_lshlrev_b32_e32 v26, 16, v27
	s_waitcnt vmcnt(0)
	v_mov_b32_e32 v15, v111
	v_and_b32_e32 v27, 0xffff0000, v27
	v_pk_mul_f32 v[26:27], v[28:29], v[26:27] op_sel_hi:[0,1]
	s_waitcnt vmcnt(0)
	v_lshlrev_b32_e32 v14, 16, v15
	v_and_b32_e32 v15, 0xffff0000, v15
	v_pk_mul_f32 v[28:29], v[28:29], v[14:15] op_sel:[1,0]
	v_add_co_u32_e32 v14, vcc, s4, v32
	s_nop 1
	v_addc_co_u32_e32 v15, vcc, -1, v33, vcc
	s_waitcnt vmcnt(0)
	v_mov_b32_e32 v15, v112
	s_waitcnt vmcnt(0)
	v_lshlrev_b32_e32 v14, 16, v15
	v_and_b32_e32 v15, 0xffff0000, v15
	v_pk_mul_f32 v[30:31], v[34:35], v[14:15] op_sel_hi:[0,1]
	s_waitcnt vmcnt(0)
	v_mov_b32_e32 v15, v113
	s_waitcnt vmcnt(0)
	v_lshlrev_b32_e32 v14, 16, v15
	s_waitcnt vmcnt(0)
	v_mov_b32_e32 v33, v114
	v_and_b32_e32 v15, 0xffff0000, v15
	v_pk_mul_f32 v[14:15], v[34:35], v[14:15] op_sel:[1,0]
	ds_read_b32 v34, v141 offset:60
	s_waitcnt vmcnt(0)
	v_lshlrev_b32_e32 v32, 16, v33
	v_and_b32_e32 v33, 0xffff0000, v33
	s_waitcnt lgkmcnt(0)
	v_pk_mul_f32 v[34:35], v[34:35], v[32:33] op_sel_hi:[0,1]
	s_branch .LBB0_620

.LBB0_645:
	s_or_b64 exec, exec, s[12:13]
	s_andn2_b64 vcc, exec, s[10:11]
	s_mov_b32 s24, 0x3d800000
	s_waitcnt lgkmcnt(0)
	s_barrier
	s_cbranch_vccnz .LBB0_647
	s_ashr_i32 s9, s8, 31
	s_lshl_b64 s[4:5], s[8:9], 12
	v_lshl_add_u64 v[0:1], v[8:9], 0, s[4:5]
	v_add_co_u32_e32 v150, vcc, 0xffff2000, v0
	s_nop 1
	v_addc_co_u32_e32 v151, vcc, -1, v1, vcc
	v_add_co_u32_e32 v152, vcc, 0xffff4000, v0
	s_nop 1
	v_addc_co_u32_e32 v153, vcc, -1, v1, vcc
	v_add_co_u32_e32 v154, vcc, 0xffff6000, v0
	s_nop 1
	v_addc_co_u32_e32 v155, vcc, -1, v1, vcc
	v_add_co_u32_e32 v156, vcc, 0xffff8000, v0
	s_nop 1
	v_addc_co_u32_e32 v157, vcc, -1, v1, vcc
	v_add_co_u32_e32 v158, vcc, 0xffffa000, v0
	s_nop 1
	v_addc_co_u32_e32 v159, vcc, -1, v1, vcc
	v_add_co_u32_e32 v160, vcc, 0xffffc000, v0
	s_nop 1
	v_addc_co_u32_e32 v161, vcc, -1, v1, vcc
	v_add_co_u32_e32 v162, vcc, 0xffffe000, v0
	s_nop 1
	v_addc_co_u32_e32 v163, vcc, -1, v1, vcc
	global_load_dwordx2 v[100:101], v[150:151], off offset:-4096
	global_load_dwordx2 v[102:103], v[150:151], off
	global_load_dwordx2 v[104:105], v[152:153], off offset:-4096
	global_load_dwordx2 v[106:107], v[152:153], off
	global_load_dwordx2 v[108:109], v[154:155], off offset:-4096
	global_load_dwordx2 v[110:111], v[154:155], off
	global_load_dwordx2 v[112:113], v[156:157], off offset:-4096
	global_load_dwordx2 v[114:115], v[156:157], off
	global_load_dwordx2 v[116:117], v[158:159], off offset:-4096
	global_load_dwordx2 v[118:119], v[158:159], off
	global_load_dwordx2 v[120:121], v[160:161], off offset:-4096
	global_load_dwordx2 v[122:123], v[160:161], off
	global_load_dwordx2 v[124:125], v[162:163], off offset:-4096
	global_load_dwordx2 v[126:127], v[162:163], off
	global_load_dwordx2 v[128:129], v[0:1], off offset:-4096
	v_add_co_u32_e32 v2, vcc, 0xffff1000, v0
	ds_read2_b32 v[4:5], v141 offset0:1 offset1:2
	s_nop 0
	v_addc_co_u32_e32 v3, vcc, -1, v1, vcc
	s_waitcnt vmcnt(0)
	v_mov_b32_e32 v2, v100
	v_mov_b32_e32 v3, v101
	s_movk_i32 s4, 0x9000
	s_movk_i32 s2, 0xb000
	s_waitcnt vmcnt(0) lgkmcnt(0)
	v_pk_mul_f32 v[66:67], v[2:3], v[4:5] op_sel_hi:[1,0]
	v_add_co_u32_e32 v2, vcc, 0xffff2000, v0
	s_nop 1
	v_addc_co_u32_e32 v3, vcc, -1, v1, vcc
	s_waitcnt vmcnt(0)
	v_mov_b32_e32 v2, v102
	v_mov_b32_e32 v3, v103
	s_waitcnt vmcnt(0)
	v_pk_mul_f32 v[64:65], v[2:3], v[4:5] op_sel:[0,1]
	v_add_co_u32_e32 v2, vcc, 0xffff3000, v0
	ds_read2_b32 v[4:5], v141 offset0:3 offset1:4
	s_nop 0
	v_addc_co_u32_e32 v3, vcc, -1, v1, vcc
	s_waitcnt vmcnt(0)
	v_mov_b32_e32 v2, v104
	v_mov_b32_e32 v3, v105
	s_waitcnt vmcnt(0) lgkmcnt(0)
	v_pk_mul_f32 v[62:63], v[2:3], v[4:5] op_sel_hi:[1,0]
	v_add_co_u32_e32 v2, vcc, 0xffff4000, v0
	s_nop 1
	v_addc_co_u32_e32 v3, vcc, -1, v1, vcc
	s_waitcnt vmcnt(0)
	v_mov_b32_e32 v2, v106
	v_mov_b32_e32 v3, v107
	s_waitcnt vmcnt(0)
	v_pk_mul_f32 v[60:61], v[2:3], v[4:5] op_sel:[0,1]
	v_add_co_u32_e32 v2, vcc, 0xffff5000, v0
	ds_read2_b32 v[4:5], v141 offset0:5 offset1:6
	s_nop 0
	v_addc_co_u32_e32 v3, vcc, -1, v1, vcc
	s_waitcnt vmcnt(0)
	v_mov_b32_e32 v2, v108
	v_mov_b32_e32 v3, v109
	s_waitcnt vmcnt(0) lgkmcnt(0)
	v_pk_mul_f32 v[56:57], v[2:3], v[4:5] op_sel_hi:[1,0]
	v_add_co_u32_e32 v2, vcc, 0xffff6000, v0
	s_nop 1
	v_addc_co_u32_e32 v3, vcc, -1, v1, vcc
	s_waitcnt vmcnt(0)
	v_mov_b32_e32 v2, v110
	v_mov_b32_e32 v3, v111
	s_waitcnt vmcnt(0)
	v_pk_mul_f32 v[52:53], v[2:3], v[4:5] op_sel:[0,1]
	v_add_co_u32_e32 v2, vcc, 0xffff7000, v0
	ds_read2_b32 v[4:5], v141 offset0:7 offset1:8
	s_nop 0
	v_addc_co_u32_e32 v3, vcc, -1, v1, vcc
	s_waitcnt vmcnt(0)
	v_mov_b32_e32 v2, v112
	v_mov_b32_e32 v3, v113
	s_waitcnt vmcnt(0) lgkmcnt(0)
	v_pk_mul_f32 v[54:55], v[2:3], v[4:5] op_sel_hi:[1,0]
	v_add_co_u32_e32 v2, vcc, s4, v0
	s_nop 1
	v_addc_co_u32_e32 v3, vcc, -1, v1, vcc
	s_waitcnt vmcnt(0)
	v_mov_b32_e32 v6, v114
	v_mov_b32_e32 v7, v115
	s_waitcnt vmcnt(0)
	v_pk_mul_f32 v[50:51], v[6:7], v[4:5] op_sel:[0,1]
	s_waitcnt vmcnt(0)
	v_mov_b32_e32 v2, v116
	v_mov_b32_e32 v3, v117
	ds_read2_b32 v[4:5], v141 offset0:9 offset1:10
	s_waitcnt vmcnt(0) lgkmcnt(0)
	v_pk_mul_f32 v[44:45], v[2:3], v[4:5] op_sel_hi:[1,0]
	v_add_co_u32_e32 v2, vcc, s2, v0
	s_movk_i32 s2, 0xc000
	s_nop 0
	v_addc_co_u32_e32 v3, vcc, -1, v1, vcc
	s_waitcnt vmcnt(0)
	v_mov_b32_e32 v6, v118
	v_mov_b32_e32 v7, v119
	s_waitcnt vmcnt(0)
	v_pk_mul_f32 v[46:47], v[6:7], v[4:5] op_sel:[0,1]
	s_waitcnt vmcnt(0)
	v_mov_b32_e32 v2, v120
	v_mov_b32_e32 v3, v121
	ds_read2_b32 v[4:5], v141 offset0:11 offset1:12
	s_waitcnt vmcnt(0) lgkmcnt(0)
	v_pk_mul_f32 v[42:43], v[2:3], v[4:5] op_sel_hi:[1,0]
	v_add_co_u32_e32 v2, vcc, s2, v0
	s_nop 1
	v_addc_co_u32_e32 v3, vcc, -1, v1, vcc
	s_waitcnt vmcnt(0)
	v_mov_b32_e32 v2, v122
	v_mov_b32_e32 v3, v123
	s_waitcnt vmcnt(0)
	v_pk_mul_f32 v[38:39], v[2:3], v[4:5] op_sel:[0,1]
	v_add_co_u32_e32 v2, vcc, 0xffffd000, v0
	ds_read2_b32 v[4:5], v141 offset0:13 offset1:14
	s_nop 0
	v_addc_co_u32_e32 v3, vcc, -1, v1, vcc
	s_waitcnt vmcnt(0)
	v_mov_b32_e32 v2, v124
	v_mov_b32_e32 v3, v125
	s_waitcnt vmcnt(0) lgkmcnt(0)
	v_pk_mul_f32 v[34:35], v[2:3], v[4:5] op_sel_hi:[1,0]
	v_add_co_u32_e32 v2, vcc, 0xffffe000, v0
	s_nop 1
	v_addc_co_u32_e32 v3, vcc, -1, v1, vcc
	s_waitcnt vmcnt(0)
	v_mov_b32_e32 v2, v126
	v_mov_b32_e32 v3, v127
	s_nop 0
	s_waitcnt vmcnt(0)
	v_mov_b32_e32 v0, v128
	v_mov_b32_e32 v1, v129
	s_waitcnt vmcnt(1)
	v_pk_mul_f32 v[22:23], v[2:3], v[4:5] op_sel:[0,1]
	ds_read_b32 v2, v141 offset:60
	s_waitcnt vmcnt(0) lgkmcnt(0)
	v_pk_mul_f32 v[36:37], v[0:1], v[2:3] op_sel_hi:[1,0]
	s_branch .LBB0_648
